# gate/up output O stored chunk-major ([K/8][tokens][8]): SwiGLU epilogue stores 256 contiguous bytes per 16 lanes without the LDS transpose; down-projection A operand chunk-major in global memory and L
# speedup vs baseline: 1.0162x; 1.0031x over previous
; __device__ __forceinline__ unsigned cvt_pk_bf16(float lo, float hi) { f32x2_t v = {lo, hi}; bf16x2_t b = __builtin_convertvector(v, bf16x2_t); return __builtin_bit_cast(unsigned, b); }
; __device__ __forceinline__ float silu_mul(float a, float b) { return a * b * __builtin_amdgcn_rcpf(1.0f + __builtin_amdgcn_exp2f(a * -1.4426950408889634f)); }
;     __device__ __forceinline__ void operator()(const f32x4 (&acc)[2][2][4][2], const Unit& u, int wr, int wc, int fr, int fq, const float (&rr)[2][4]) const {
;         const int row0 = u.pm * BM + wr * 64 + fr, col0 = u.pn * 128 + wc * 32 + 8 * fq;
; #pragma unroll
;         for (int ai = 0; ai < 2; ++ai)
; #pragma unroll
;             for (int m = 0; m < 4; ++m) { const int row = row0 + ai * HALF + m * 16; const float r = rr[ai][m];
;                 const f32x4 g0 = acc[ai][0][m][0] * r, g1 = acc[ai][0][m][1] * r, u0 = acc[ai][1][m][0] * r, u1 = acc[ai][1][m][1] * r;
;                 u32x4 w; w.x = cvt_pk_bf16(silu_mul(g0[0], u0[0]), silu_mul(g0[1], u0[1])); w.y = cvt_pk_bf16(silu_mul(g0[2], u0[2]), silu_mul(g0[3], u0[3]));
;                 w.z = cvt_pk_bf16(silu_mul(g1[0], u1[0]), silu_mul(g1[1], u1[1])); w.w = cvt_pk_bf16(silu_mul(g1[2], u1[2]), silu_mul(g1[3], u1[3]));
;                 *(u32x4*)(O + (size_t)row * ldc + col0) = w; }
.LBB0_616:
	s_lshl_b32 s6, s23, 8
	s_add_i32 s6, s6, s2
	v_add_u32_e32 v155, s6, v141
	v_lshrrev_b32_e32 v158, 3, v153
	v_lshl_or_b32 v158, s22, 4, v158
	v_lshlrev_b32_e32 v158, 18, v158
	v_lshl_or_b32 v158, v155, 4, v158
	v_mov_b32_e32 v159, 0
	v_mov_b32_e32 v156, 1.0
	v_mov_b32_e32 v157, 1.0
	v_lshl_add_u64 v[158:159], s[56:57], 0, v[158:159]
	s_bitcmp1_b32 s101, 1
	s_cbranch_scc1 .Lepi_h1
	v_cvt_f32_f16_e32 v140, v143
	v_pk_mul_f32 v[118:119], v[126:127], v[118:119]
	v_pk_mul_f32 v[120:121], v[128:129], v[120:121]
	v_pk_mul_f32 v[114:115], v[122:123], v[114:115]
	v_pk_mul_f32 v[116:117], v[124:125], v[116:117]
	v_mul_f32_e32 v142, 0xbfb8aa3b, v140
	v_mul_f32_e32 v144, v140, v140
	v_pk_mul_f32 v[126:127], v[126:127], v[142:143] op_sel_hi:[1,0]
	v_pk_mul_f32 v[128:129], v[128:129], v[142:143] op_sel_hi:[1,0]
	v_pk_mul_f32 v[122:123], v[122:123], v[142:143] op_sel_hi:[1,0]
	v_pk_mul_f32 v[124:125], v[124:125], v[142:143] op_sel_hi:[1,0]
	v_exp_f32_e32 v126, v126
	v_exp_f32_e32 v127, v127
	v_exp_f32_e32 v128, v128
	v_exp_f32_e32 v129, v129
	v_exp_f32_e32 v122, v122
	v_exp_f32_e32 v123, v123
	v_exp_f32_e32 v124, v124
	v_exp_f32_e32 v125, v125
	v_pk_mul_f32 v[118:119], v[118:119], v[144:145] op_sel_hi:[1,0]
	v_pk_mul_f32 v[120:121], v[120:121], v[144:145] op_sel_hi:[1,0]
	v_pk_mul_f32 v[114:115], v[114:115], v[144:145] op_sel_hi:[1,0]
	v_pk_mul_f32 v[116:117], v[116:117], v[144:145] op_sel_hi:[1,0]
	v_pk_add_f32 v[126:127], v[126:127], v[156:157]
	v_pk_add_f32 v[128:129], v[128:129], v[156:157]
	v_pk_add_f32 v[122:123], v[122:123], v[156:157]
	v_pk_add_f32 v[124:125], v[124:125], v[156:157]
	v_rcp_f32_e32 v126, v126
	v_rcp_f32_e32 v127, v127
	v_rcp_f32_e32 v128, v128
	v_rcp_f32_e32 v129, v129
	v_rcp_f32_e32 v122, v122
	v_rcp_f32_e32 v123, v123
	v_rcp_f32_e32 v124, v124
	v_rcp_f32_e32 v125, v125
	s_nop 0
	v_pk_mul_f32 v[118:119], v[118:119], v[126:127]
	v_pk_mul_f32 v[120:121], v[120:121], v[128:129]
	v_pk_mul_f32 v[114:115], v[114:115], v[122:123]
	v_pk_mul_f32 v[116:117], v[116:117], v[124:125]
	v_cvt_pk_bf16_f32 v118, v118, v119
	v_cvt_pk_bf16_f32 v119, v120, v121
	v_cvt_pk_bf16_f32 v120, v114, v115
	v_cvt_pk_bf16_f32 v121, v116, v117
	global_store_dwordx4 v[158:159], v[118:121], off
	v_cvt_f32_f16_e32 v140, v145
	v_pk_mul_f32 v[102:103], v[110:111], v[102:103]
	v_pk_mul_f32 v[104:105], v[112:113], v[104:105]
	v_pk_mul_f32 v[98:99], v[106:107], v[98:99]
	v_pk_mul_f32 v[100:101], v[108:109], v[100:101]
	v_mul_f32_e32 v142, 0xbfb8aa3b, v140
	v_mul_f32_e32 v144, v140, v140
	v_pk_mul_f32 v[110:111], v[110:111], v[142:143] op_sel_hi:[1,0]
	v_pk_mul_f32 v[112:113], v[112:113], v[142:143] op_sel_hi:[1,0]
	v_pk_mul_f32 v[106:107], v[106:107], v[142:143] op_sel_hi:[1,0]
	v_pk_mul_f32 v[108:109], v[108:109], v[142:143] op_sel_hi:[1,0]
	v_exp_f32_e32 v110, v110
	v_exp_f32_e32 v111, v111
	v_exp_f32_e32 v112, v112
	v_exp_f32_e32 v113, v113
	v_exp_f32_e32 v106, v106
	v_exp_f32_e32 v107, v107
	v_exp_f32_e32 v108, v108
	v_exp_f32_e32 v109, v109
	v_pk_mul_f32 v[102:103], v[102:103], v[144:145] op_sel_hi:[1,0]
	v_pk_mul_f32 v[104:105], v[104:105], v[144:145] op_sel_hi:[1,0]
	v_pk_mul_f32 v[98:99], v[98:99], v[144:145] op_sel_hi:[1,0]
	v_pk_mul_f32 v[100:101], v[100:101], v[144:145] op_sel_hi:[1,0]
	v_pk_add_f32 v[110:111], v[110:111], v[156:157]
	v_pk_add_f32 v[112:113], v[112:113], v[156:157]
	v_pk_add_f32 v[106:107], v[106:107], v[156:157]
	v_pk_add_f32 v[108:109], v[108:109], v[156:157]
	v_rcp_f32_e32 v110, v110
	v_rcp_f32_e32 v111, v111
	v_rcp_f32_e32 v112, v112
	v_rcp_f32_e32 v113, v113
	v_rcp_f32_e32 v106, v106
	v_rcp_f32_e32 v107, v107
	v_rcp_f32_e32 v108, v108
	v_rcp_f32_e32 v109, v109
	s_nop 0
	v_pk_mul_f32 v[102:103], v[102:103], v[110:111]
	v_pk_mul_f32 v[104:105], v[104:105], v[112:113]
	v_pk_mul_f32 v[98:99], v[98:99], v[106:107]
	v_pk_mul_f32 v[100:101], v[100:101], v[108:109]
	v_cvt_pk_bf16_f32 v102, v102, v103
	v_cvt_pk_bf16_f32 v103, v104, v105
	v_cvt_pk_bf16_f32 v104, v98, v99
	v_cvt_pk_bf16_f32 v105, v100, v101
	global_store_dwordx4 v[158:159], v[102:105], off offset:256
	v_cvt_f32_f16_e32 v140, v147
	v_pk_mul_f32 v[86:87], v[94:95], v[86:87]
	v_pk_mul_f32 v[88:89], v[96:97], v[88:89]
	v_pk_mul_f32 v[82:83], v[90:91], v[82:83]
	v_pk_mul_f32 v[84:85], v[92:93], v[84:85]
	v_mul_f32_e32 v142, 0xbfb8aa3b, v140
	v_mul_f32_e32 v144, v140, v140
	v_pk_mul_f32 v[94:95], v[94:95], v[142:143] op_sel_hi:[1,0]
	v_pk_mul_f32 v[96:97], v[96:97], v[142:143] op_sel_hi:[1,0]
	v_pk_mul_f32 v[90:91], v[90:91], v[142:143] op_sel_hi:[1,0]
	v_pk_mul_f32 v[92:93], v[92:93], v[142:143] op_sel_hi:[1,0]
	v_exp_f32_e32 v94, v94
	v_exp_f32_e32 v95, v95
	v_exp_f32_e32 v96, v96
	v_exp_f32_e32 v97, v97
	v_exp_f32_e32 v90, v90
	v_exp_f32_e32 v91, v91
	v_exp_f32_e32 v92, v92
	v_exp_f32_e32 v93, v93
	v_pk_mul_f32 v[86:87], v[86:87], v[144:145] op_sel_hi:[1,0]
	v_pk_mul_f32 v[88:89], v[88:89], v[144:145] op_sel_hi:[1,0]
	v_pk_mul_f32 v[82:83], v[82:83], v[144:145] op_sel_hi:[1,0]
	v_pk_mul_f32 v[84:85], v[84:85], v[144:145] op_sel_hi:[1,0]
	v_pk_add_f32 v[94:95], v[94:95], v[156:157]
	v_pk_add_f32 v[96:97], v[96:97], v[156:157]
	v_pk_add_f32 v[90:91], v[90:91], v[156:157]
	v_pk_add_f32 v[92:93], v[92:93], v[156:157]
	v_rcp_f32_e32 v94, v94
	v_rcp_f32_e32 v95, v95
	v_rcp_f32_e32 v96, v96
	v_rcp_f32_e32 v97, v97
	v_rcp_f32_e32 v90, v90
	v_rcp_f32_e32 v91, v91
	v_rcp_f32_e32 v92, v92
	v_rcp_f32_e32 v93, v93
	s_nop 0
	v_pk_mul_f32 v[86:87], v[86:87], v[94:95]
	v_pk_mul_f32 v[88:89], v[88:89], v[96:97]
	v_pk_mul_f32 v[82:83], v[82:83], v[90:91]
	v_pk_mul_f32 v[84:85], v[84:85], v[92:93]
	v_cvt_pk_bf16_f32 v86, v86, v87
	v_cvt_pk_bf16_f32 v87, v88, v89
	v_cvt_pk_bf16_f32 v88, v82, v83
; __device__ __forceinline__ unsigned cvt_pk_bf16(float lo, float hi) { f32x2_t v = {lo, hi}; bf16x2_t b = __builtin_convertvector(v, bf16x2_t); return __builtin_bit_cast(unsigned, b); }
; __device__ __forceinline__ float silu_mul(float a, float b) { return a * b * __builtin_amdgcn_rcpf(1.0f + __builtin_amdgcn_exp2f(a * -1.4426950408889634f)); }
;     __device__ __forceinline__ void operator()(const f32x4 (&acc)[2][2][4][2], const Unit& u, int wr, int wc, int fr, int fq, const float (&rr)[2][4]) const {
;     ...
;             for (int m = 0; m < 4; ++m) { const int row = row0 + ai * HALF + m * 16; const float r = rr[ai][m];
;                 const f32x4 g0 = acc[ai][0][m][0] * r, g1 = acc[ai][0][m][1] * r, u0 = acc[ai][1][m][0] * r, u1 = acc[ai][1][m][1] * r;
;                 u32x4 w; w.x = cvt_pk_bf16(silu_mul(g0[0], u0[0]), silu_mul(g0[1], u0[1])); w.y = cvt_pk_bf16(silu_mul(g0[2], u0[2]), silu_mul(g0[3], u0[3]));
;                 w.z = cvt_pk_bf16(silu_mul(g1[0], u1[0]), silu_mul(g1[1], u1[1])); w.w = cvt_pk_bf16(silu_mul(g1[2], u1[2]), silu_mul(g1[3], u1[3]));
;                 *(u32x4*)(O + (size_t)row * ldc + col0) = w; }
	v_cvt_pk_bf16_f32 v89, v84, v85
	global_store_dwordx4 v[158:159], v[86:89], off offset:512
	v_cvt_f32_f16_e32 v140, v149
	v_pk_mul_f32 v[70:71], v[78:79], v[70:71]
	v_pk_mul_f32 v[72:73], v[80:81], v[72:73]
	v_pk_mul_f32 v[66:67], v[74:75], v[66:67]
	v_pk_mul_f32 v[68:69], v[76:77], v[68:69]
	v_mul_f32_e32 v142, 0xbfb8aa3b, v140
	v_mul_f32_e32 v144, v140, v140
	v_pk_mul_f32 v[78:79], v[78:79], v[142:143] op_sel_hi:[1,0]
	v_pk_mul_f32 v[80:81], v[80:81], v[142:143] op_sel_hi:[1,0]
	v_pk_mul_f32 v[74:75], v[74:75], v[142:143] op_sel_hi:[1,0]
	v_pk_mul_f32 v[76:77], v[76:77], v[142:143] op_sel_hi:[1,0]
	v_exp_f32_e32 v78, v78
	v_exp_f32_e32 v79, v79
	v_exp_f32_e32 v80, v80
	v_exp_f32_e32 v81, v81
	v_exp_f32_e32 v74, v74
	v_exp_f32_e32 v75, v75
	v_exp_f32_e32 v76, v76
	v_exp_f32_e32 v77, v77
	v_pk_mul_f32 v[70:71], v[70:71], v[144:145] op_sel_hi:[1,0]
	v_pk_mul_f32 v[72:73], v[72:73], v[144:145] op_sel_hi:[1,0]
	v_pk_mul_f32 v[66:67], v[66:67], v[144:145] op_sel_hi:[1,0]
	v_pk_mul_f32 v[68:69], v[68:69], v[144:145] op_sel_hi:[1,0]
	v_pk_add_f32 v[78:79], v[78:79], v[156:157]
	v_pk_add_f32 v[80:81], v[80:81], v[156:157]
	v_pk_add_f32 v[74:75], v[74:75], v[156:157]
	v_pk_add_f32 v[76:77], v[76:77], v[156:157]
	v_rcp_f32_e32 v78, v78
	v_rcp_f32_e32 v79, v79
	v_rcp_f32_e32 v80, v80
	v_rcp_f32_e32 v81, v81
	v_rcp_f32_e32 v74, v74
	v_rcp_f32_e32 v75, v75
	v_rcp_f32_e32 v76, v76
	v_rcp_f32_e32 v77, v77
	s_nop 0
	v_pk_mul_f32 v[70:71], v[70:71], v[78:79]
	v_pk_mul_f32 v[72:73], v[72:73], v[80:81]
	v_pk_mul_f32 v[66:67], v[66:67], v[74:75]
	v_pk_mul_f32 v[68:69], v[68:69], v[76:77]
	v_cvt_pk_bf16_f32 v70, v70, v71
	v_cvt_pk_bf16_f32 v71, v72, v73
	v_cvt_pk_bf16_f32 v72, v66, v67
	v_cvt_pk_bf16_f32 v73, v68, v69
	global_store_dwordx4 v[158:159], v[70:73], off offset:768
; __device__ __forceinline__ unsigned cvt_pk_bf16(float lo, float hi) { f32x2_t v = {lo, hi}; bf16x2_t b = __builtin_convertvector(v, bf16x2_t); return __builtin_bit_cast(unsigned, b); }
; __device__ __forceinline__ float silu_mul(float a, float b) { return a * b * __builtin_amdgcn_rcpf(1.0f + __builtin_amdgcn_exp2f(a * -1.4426950408889634f)); }
;     __device__ __forceinline__ void operator()(const f32x4 (&acc)[2][2][4][2], const Unit& u, int wr, int wc, int fr, int fq, const float (&rr)[2][4]) const {
;     ...
;         for (int ai = 0; ai < 2; ++ai)
; #pragma unroll
;             for (int m = 0; m < 4; ++m) { const int row = row0 + ai * HALF + m * 16; const float r = rr[ai][m];
;                 const f32x4 g0 = acc[ai][0][m][0] * r, g1 = acc[ai][0][m][1] * r, u0 = acc[ai][1][m][0] * r, u1 = acc[ai][1][m][1] * r;
;                 u32x4 w; w.x = cvt_pk_bf16(silu_mul(g0[0], u0[0]), silu_mul(g0[1], u0[1])); w.y = cvt_pk_bf16(silu_mul(g0[2], u0[2]), silu_mul(g0[3], u0[3]));
;                 w.z = cvt_pk_bf16(silu_mul(g1[0], u1[0]), silu_mul(g1[1], u1[1])); w.w = cvt_pk_bf16(silu_mul(g1[2], u1[2]), silu_mul(g1[3], u1[3]));
;                 *(u32x4*)(O + (size_t)row * ldc + col0) = w; }
.Lepi_h1:
	s_bitcmp1_b32 s101, 0
	s_cbranch_scc1 .Lepi_end
	v_cvt_f32_f16_sdwa v140, v143 dst_sel:DWORD dst_unused:UNUSED_PAD src0_sel:WORD_1
	v_pk_mul_f32 v[54:55], v[62:63], v[54:55]
	v_pk_mul_f32 v[56:57], v[64:65], v[56:57]
	v_pk_mul_f32 v[50:51], v[58:59], v[50:51]
	v_pk_mul_f32 v[52:53], v[60:61], v[52:53]
	v_mul_f32_e32 v142, 0xbfb8aa3b, v140
	v_mul_f32_e32 v144, v140, v140
	v_pk_mul_f32 v[62:63], v[62:63], v[142:143] op_sel_hi:[1,0]
	v_pk_mul_f32 v[64:65], v[64:65], v[142:143] op_sel_hi:[1,0]
	v_pk_mul_f32 v[58:59], v[58:59], v[142:143] op_sel_hi:[1,0]
	v_pk_mul_f32 v[60:61], v[60:61], v[142:143] op_sel_hi:[1,0]
	v_exp_f32_e32 v62, v62
	v_exp_f32_e32 v63, v63
	v_exp_f32_e32 v64, v64
	v_exp_f32_e32 v65, v65
	v_exp_f32_e32 v58, v58
	v_exp_f32_e32 v59, v59
	v_exp_f32_e32 v60, v60
	v_exp_f32_e32 v61, v61
	v_pk_mul_f32 v[54:55], v[54:55], v[144:145] op_sel_hi:[1,0]
	v_pk_mul_f32 v[56:57], v[56:57], v[144:145] op_sel_hi:[1,0]
	v_pk_mul_f32 v[50:51], v[50:51], v[144:145] op_sel_hi:[1,0]
	v_pk_mul_f32 v[52:53], v[52:53], v[144:145] op_sel_hi:[1,0]
	v_pk_add_f32 v[62:63], v[62:63], v[156:157]
	v_pk_add_f32 v[64:65], v[64:65], v[156:157]
	v_pk_add_f32 v[58:59], v[58:59], v[156:157]
	v_pk_add_f32 v[60:61], v[60:61], v[156:157]
	v_rcp_f32_e32 v62, v62
	v_rcp_f32_e32 v63, v63
	v_rcp_f32_e32 v64, v64
	v_rcp_f32_e32 v65, v65
	v_rcp_f32_e32 v58, v58
	v_rcp_f32_e32 v59, v59
	v_rcp_f32_e32 v60, v60
	v_rcp_f32_e32 v61, v61
	s_nop 0
	v_pk_mul_f32 v[54:55], v[54:55], v[62:63]
	v_pk_mul_f32 v[56:57], v[56:57], v[64:65]
	v_pk_mul_f32 v[50:51], v[50:51], v[58:59]
	v_pk_mul_f32 v[52:53], v[52:53], v[60:61]
	v_cvt_pk_bf16_f32 v54, v54, v55
	v_cvt_pk_bf16_f32 v55, v56, v57
	v_cvt_pk_bf16_f32 v56, v50, v51
	v_cvt_pk_bf16_f32 v57, v52, v53
	global_store_dwordx4 v[158:159], v[54:57], off offset:2048
	v_cvt_f32_f16_sdwa v140, v145 dst_sel:DWORD dst_unused:UNUSED_PAD src0_sel:WORD_1
	v_pk_mul_f32 v[38:39], v[46:47], v[38:39]
	v_pk_mul_f32 v[40:41], v[48:49], v[40:41]
	v_pk_mul_f32 v[34:35], v[42:43], v[34:35]
	v_pk_mul_f32 v[36:37], v[44:45], v[36:37]
	v_mul_f32_e32 v142, 0xbfb8aa3b, v140
	v_mul_f32_e32 v144, v140, v140
	v_pk_mul_f32 v[46:47], v[46:47], v[142:143] op_sel_hi:[1,0]
	v_pk_mul_f32 v[48:49], v[48:49], v[142:143] op_sel_hi:[1,0]
	v_pk_mul_f32 v[42:43], v[42:43], v[142:143] op_sel_hi:[1,0]
	v_pk_mul_f32 v[44:45], v[44:45], v[142:143] op_sel_hi:[1,0]
	v_exp_f32_e32 v46, v46
	v_exp_f32_e32 v47, v47
	v_exp_f32_e32 v48, v48
	v_exp_f32_e32 v49, v49
	v_exp_f32_e32 v42, v42
	v_exp_f32_e32 v43, v43
	v_exp_f32_e32 v44, v44
	v_exp_f32_e32 v45, v45
	v_pk_mul_f32 v[38:39], v[38:39], v[144:145] op_sel_hi:[1,0]
	v_pk_mul_f32 v[40:41], v[40:41], v[144:145] op_sel_hi:[1,0]
	v_pk_mul_f32 v[34:35], v[34:35], v[144:145] op_sel_hi:[1,0]
	v_pk_mul_f32 v[36:37], v[36:37], v[144:145] op_sel_hi:[1,0]
	v_pk_add_f32 v[46:47], v[46:47], v[156:157]
	v_pk_add_f32 v[48:49], v[48:49], v[156:157]
	v_pk_add_f32 v[42:43], v[42:43], v[156:157]
	v_pk_add_f32 v[44:45], v[44:45], v[156:157]
	v_rcp_f32_e32 v46, v46
	v_rcp_f32_e32 v47, v47
	v_rcp_f32_e32 v48, v48
	v_rcp_f32_e32 v49, v49
	v_rcp_f32_e32 v42, v42
	v_rcp_f32_e32 v43, v43
	v_rcp_f32_e32 v44, v44
	v_rcp_f32_e32 v45, v45
	s_nop 0
	v_pk_mul_f32 v[38:39], v[38:39], v[46:47]
	v_pk_mul_f32 v[40:41], v[40:41], v[48:49]
	v_pk_mul_f32 v[34:35], v[34:35], v[42:43]
	v_pk_mul_f32 v[36:37], v[36:37], v[44:45]
	v_cvt_pk_bf16_f32 v38, v38, v39
	v_cvt_pk_bf16_f32 v39, v40, v41
	v_cvt_pk_bf16_f32 v40, v34, v35
	v_cvt_pk_bf16_f32 v41, v36, v37
	global_store_dwordx4 v[158:159], v[38:41], off offset:2304
	v_cvt_f32_f16_sdwa v140, v147 dst_sel:DWORD dst_unused:UNUSED_PAD src0_sel:WORD_1
	v_pk_mul_f32 v[22:23], v[30:31], v[22:23]
	v_pk_mul_f32 v[24:25], v[32:33], v[24:25]
	v_pk_mul_f32 v[18:19], v[26:27], v[18:19]
	v_pk_mul_f32 v[20:21], v[28:29], v[20:21]
	v_mul_f32_e32 v142, 0xbfb8aa3b, v140
	v_mul_f32_e32 v144, v140, v140
	v_pk_mul_f32 v[30:31], v[30:31], v[142:143] op_sel_hi:[1,0]
	v_pk_mul_f32 v[32:33], v[32:33], v[142:143] op_sel_hi:[1,0]
	v_pk_mul_f32 v[26:27], v[26:27], v[142:143] op_sel_hi:[1,0]
	v_pk_mul_f32 v[28:29], v[28:29], v[142:143] op_sel_hi:[1,0]
	v_exp_f32_e32 v30, v30
	v_exp_f32_e32 v31, v31
	v_exp_f32_e32 v32, v32
	v_exp_f32_e32 v33, v33
	v_exp_f32_e32 v26, v26
	v_exp_f32_e32 v27, v27
	v_exp_f32_e32 v28, v28
	v_exp_f32_e32 v29, v29
	v_pk_mul_f32 v[22:23], v[22:23], v[144:145] op_sel_hi:[1,0]
	v_pk_mul_f32 v[24:25], v[24:25], v[144:145] op_sel_hi:[1,0]
	v_pk_mul_f32 v[18:19], v[18:19], v[144:145] op_sel_hi:[1,0]
	v_pk_mul_f32 v[20:21], v[20:21], v[144:145] op_sel_hi:[1,0]
	v_pk_add_f32 v[30:31], v[30:31], v[156:157]
	v_pk_add_f32 v[32:33], v[32:33], v[156:157]
	v_pk_add_f32 v[26:27], v[26:27], v[156:157]
	v_pk_add_f32 v[28:29], v[28:29], v[156:157]
	v_rcp_f32_e32 v30, v30
	v_rcp_f32_e32 v31, v31
	v_rcp_f32_e32 v32, v32
	v_rcp_f32_e32 v33, v33
	v_rcp_f32_e32 v26, v26
	v_rcp_f32_e32 v27, v27
	v_rcp_f32_e32 v28, v28
	v_rcp_f32_e32 v29, v29
	s_nop 0
	v_pk_mul_f32 v[22:23], v[22:23], v[30:31]
	v_pk_mul_f32 v[24:25], v[24:25], v[32:33]
	v_pk_mul_f32 v[18:19], v[18:19], v[26:27]
	v_pk_mul_f32 v[20:21], v[20:21], v[28:29]
	v_cvt_pk_bf16_f32 v22, v22, v23
	v_cvt_pk_bf16_f32 v23, v24, v25
	v_cvt_pk_bf16_f32 v24, v18, v19
	v_cvt_pk_bf16_f32 v25, v20, v21
	global_store_dwordx4 v[158:159], v[22:25], off offset:2560
	v_cvt_f32_f16_sdwa v140, v149 dst_sel:DWORD dst_unused:UNUSED_PAD src0_sel:WORD_1
	v_pk_mul_f32 v[6:7], v[14:15], v[6:7]
	v_pk_mul_f32 v[8:9], v[16:17], v[8:9]
	v_pk_mul_f32 v[2:3], v[10:11], v[2:3]
	v_pk_mul_f32 v[4:5], v[12:13], v[4:5]
	v_mul_f32_e32 v142, 0xbfb8aa3b, v140
	v_mul_f32_e32 v144, v140, v140
	v_pk_mul_f32 v[14:15], v[14:15], v[142:143] op_sel_hi:[1,0]
	v_pk_mul_f32 v[16:17], v[16:17], v[142:143] op_sel_hi:[1,0]
	v_pk_mul_f32 v[10:11], v[10:11], v[142:143] op_sel_hi:[1,0]
	v_pk_mul_f32 v[12:13], v[12:13], v[142:143] op_sel_hi:[1,0]
	v_exp_f32_e32 v14, v14
	v_exp_f32_e32 v15, v15
	v_exp_f32_e32 v16, v16
	v_exp_f32_e32 v17, v17
	v_exp_f32_e32 v10, v10
	v_exp_f32_e32 v11, v11
	v_exp_f32_e32 v12, v12
	v_exp_f32_e32 v13, v13
	v_pk_mul_f32 v[6:7], v[6:7], v[144:145] op_sel_hi:[1,0]
	v_pk_mul_f32 v[8:9], v[8:9], v[144:145] op_sel_hi:[1,0]
	v_pk_mul_f32 v[2:3], v[2:3], v[144:145] op_sel_hi:[1,0]
	v_pk_mul_f32 v[4:5], v[4:5], v[144:145] op_sel_hi:[1,0]
	v_pk_add_f32 v[14:15], v[14:15], v[156:157]
	v_pk_add_f32 v[16:17], v[16:17], v[156:157]
	v_pk_add_f32 v[10:11], v[10:11], v[156:157]
	v_pk_add_f32 v[12:13], v[12:13], v[156:157]
	v_rcp_f32_e32 v14, v14
	v_rcp_f32_e32 v15, v15
	v_rcp_f32_e32 v16, v16
	v_rcp_f32_e32 v17, v17
	v_rcp_f32_e32 v10, v10
	v_rcp_f32_e32 v11, v11
	v_rcp_f32_e32 v12, v12
	v_rcp_f32_e32 v13, v13
	s_nop 0
	v_pk_mul_f32 v[6:7], v[6:7], v[14:15]
	v_pk_mul_f32 v[8:9], v[8:9], v[16:17]
	v_pk_mul_f32 v[2:3], v[2:3], v[10:11]
	v_pk_mul_f32 v[4:5], v[4:5], v[12:13]
	v_cvt_pk_bf16_f32 v6, v6, v7
	v_cvt_pk_bf16_f32 v7, v8, v9
	v_cvt_pk_bf16_f32 v8, v2, v3
	v_cvt_pk_bf16_f32 v9, v4, v5
	global_store_dwordx4 v[158:159], v[6:9], off offset:2816

;     ...
;     const int tid = tid_l, wid = __builtin_amdgcn_readfirstlane(tid >> 6), lane = tid & 63, wr = wid >> 2, wc = wid & 3, fr = lane & 15, fq = lane >> 4;
;     int K_l = g.K; asm volatile("" : "+s"(K_l));
;     const int K = K_l, nt = K / BK;
;     const bf16_t* gA = g.A; const bf16_t* gB = g.Bt; asm volatile("" : "+s"(gA), "+s"(gB));
;     unsigned voffA[2], voffB[2];
; #pragma unroll
;     for (int i = 0; i < 2; ++i) { int R, C; stage_rc(tid * 16 + i * 8192, R, C); const int Rb = Epi::PERM ? ((R & ~31) + perm32(R & 31)) : R;
;         voffA[i] = (unsigned)(R * (LDA ? LDA : K) + C) * 2u; voffB[i] = (unsigned)(Rb * K + C) * 2u; }
;     const size_t kstep = (size_t)(BK * 2);
;     const size_t hstepB = (size_t)HALF * K * 2, hstepA = LDA ? (size_t)HALF * LDA * 2 : hstepB;
;     const size_t tstepA = 2 * hstepA, tstepB = 2 * hstepB; constexpr size_t acolB = (size_t)ACOL * 2;
;     const unsigned ldsw = (unsigned)wid * 1024u;
;     const int aoff = lds_byte(wr * 64 + fr, fq * 8), boff = lds_byte(wc * 32 + fr, fq * 8);
;     ...
;     Unit cur, nxt; int ui = 0;
;     if (!S.next(0, cur)) return;
;     f32x4 acc[2][2][4][2];
; #pragma unroll
;     for (int a = 0; a < 2; ++a)
; #pragma unroll
;         for (int b = 0; b < 2; ++b)
; #pragma unroll
;             for (int m = 0; m < 4; ++m)
; #pragma unroll
;                 for (int n = 0; n < 2; ++n) acc[a][b][m][n] = (f32x4){0.f, 0.f, 0.f, 0.f};
;     bf16x8 At[4][2], B0[2][2], B1[2][2];
;     typedef __fp16 h16x2 __attribute__((ext_vector_type(2)));
;     h16x2 rrp[4];
;     if constexpr (Epi::ROWSCALE) { float rr0[2][4]; row_rs8(E.ssq, cur.pm * BM + wr * 64 + fr, fq, rr0);
; #pragma unroll
;         for (int m = 0; m < 4; ++m) rrp[m] = __builtin_amdgcn_cvt_pkrtz(rr0[0][m], rr0[1][m]); }
;     const char* cA = (const char*)gA + (size_t)cur.pm * tstepA + (size_t)cur.pn * acolB; const char* cB = (const char*)gB + (size_t)cur.pn * tstepB;
;     S.a_ready(cur);
;     if constexpr (SP2) {
;         PG8_STAGE(PG8_SB(0, 0), cB, voffB); PG8_STAGE(PG8_SB(0, 1), cB + hstepB, voffB); PG8_STAGE(PG8_SA(0, 0), cA, voffA); PG8_STAGE(PG8_SA(0, 1), cA + hstepA, voffA);
;         if (wr == 1) PG8_BAR;
;         PG8_WAIT_V(2); PG8_BAR;
;         PG8_STAGE(PG8_SB(1, 0), cB + kstep, voffB); PG8_STAGE(PG8_SA(1, 0), cA + kstep, voffA); PG8_STAGE(PG8_SB(1, 1), cB + hstepB + kstep, voffB);
;         PG8_WAIT_V(6); PG8_BAR;
;     } else {
.LBB0_733:
	s_cmp_le_i32 s56, s0
	s_cselect_b64 s[2:3], -1, 0
	s_and_b64 s[2:3], s[2:3], s[4:5]
	s_andn2_b64 vcc, exec, s[2:3]
	s_cbranch_vccnz .LBB0_108
	v_readlane_b32 s0, v254, 52
	s_mul_i32 s0, s0, 0x2c0000
	s_lshl_b64 s[2:3], s[0:1], 1
	v_readlane_b32 s0, v253, 51
	s_add_u32 s4, s0, s2
	v_readlane_b32 s0, v253, 54
	s_addc_u32 s5, s0, s3
	v_readlane_b32 s2, v252, 27
	v_mov_b32_e32 v2, v0
	v_readlane_b32 s44, v252, 19
	v_readlane_b32 s3, v252, 28
	s_movk_i32 s10, 0xb00
	v_readfirstlane_b32 s20, v2
	v_readlane_b32 s45, v252, 20
	s_andn2_b64 vcc, exec, s[2:3]
	s_cbranch_vccnz .LBB0_775
	s_waitcnt lgkmcnt(0)
	v_lshlrev_b32_e32 v3, 4, v2
	v_add_u32_e32 v4, 0x2000, v3
	v_ashrrev_i32_e32 v5, 31, v4
	v_lshrrev_b32_e32 v5, 22, v5
	v_add_u32_e32 v5, v4, v5
	v_ashrrev_i32_e32 v5, 10, v5
	v_mul_i32_i24_e32 v6, 0x400, v5
	v_sub_u32_e32 v4, v4, v6
	v_lshrrev_b32_e32 v6, 4, v4
	v_bitop3_b32 v6, v6, v4, 32 bitop3:0x6c
	v_ashrrev_i32_e32 v4, 31, v6
	v_lshrrev_b32_e32 v4, 26, v4
	v_add_u32_e32 v7, v6, v4
	v_lshlrev_b32_e32 v8, 3, v5
	v_ashrrev_i32_e32 v4, 6, v7
	v_and_b32_e32 v8, 0x7ffffff0, v8
	v_add_u32_e32 v8, v4, v8
	v_lshlrev_b32_e32 v4, 5, v5
	v_and_b32_e32 v4, 32, v4
	v_mad_u64_u32 v[4:5], s[2:3], v8, s10, v[4:5]
	v_and_b32_e32 v5, 0xc0, v7
	v_sub_u32_e32 v5, v6, v5
	v_ashrrev_i16_sdwa v5, v243, sext(v5) dst_sel:DWORD dst_unused:UNUSED_PAD src0_sel:DWORD src1_sel:BYTE_0
	v_bfe_i32 v5, v5, 0, 16
	v_add_lshl_u32 v130, v4, v5, 1
	v_bfe_i32 v4, v2, 27, 1
	v_lshrrev_b32_e32 v4, 22, v4
	v_add_u32_e32 v4, v3, v4
	v_and_b32_e32 v4, 0xfffffc00, v4
	v_sub_u32_e32 v3, v3, v4
	v_lshrrev_b32_e32 v4, 4, v3
	v_ashrrev_i32_e32 v5, 31, v2
	v_bitop3_b32 v3, v4, v3, 32 bitop3:0x6c
	v_lshrrev_b32_e32 v5, 26, v5
	v_ashrrev_i32_e32 v4, 31, v3
	v_add_u32_e32 v5, v2, v5
	v_lshrrev_b32_e32 v4, 26, v4
	v_ashrrev_i32_e32 v5, 6, v5
	v_add_u32_e32 v6, v3, v4
	v_lshlrev_b32_e32 v7, 3, v5
	v_ashrrev_i32_e32 v4, 6, v6
	v_and_b32_e32 v7, 0x7ffffff0, v7
	v_add_u32_e32 v7, v4, v7
	v_lshlrev_b32_e32 v4, 5, v5
	s_ashr_i32 s11, s10, 31
	v_and_b32_e32 v4, 32, v4
	v_readlane_b32 s8, v254, 25
	s_lshl_b64 s[60:61], s[10:11], 9
	v_mad_u64_u32 v[4:5], s[2:3], v7, s10, v[4:5]
	v_readlane_b32 s9, v254, 26
	s_mul_i32 s2, s60, s9
	s_mul_hi_u32 s3, s60, s8
	s_add_i32 s6, s3, s2
	s_lshr_b64 s[2:3], s[10:11], 23
	v_readlane_b32 s12, v254, 29
	s_mul_i32 s3, s2, s8
	v_readlane_b32 s13, v254, 30
	s_add_i32 s3, s6, s3
	s_mul_i32 s6, s60, s13
	s_mul_hi_u32 s7, s60, s12
	s_ashr_i32 s16, s20, 6
	v_and_b32_e32 v5, 0xc0, v6
	s_add_i32 s6, s7, s6
	s_mul_i32 s2, s2, s12
	s_ashr_i32 s17, s20, 8
	s_lshl_b64 s[58:59], s[10:11], 8
	s_lshl_b32 s0, s16, 10
	v_sub_u32_e32 v3, v3, v5
	s_add_i32 s2, s6, s2
	s_mul_i32 s6, s60, s12
	v_ashrrev_i16_sdwa v3, v243, sext(v3) dst_sel:DWORD dst_unused:UNUSED_PAD src0_sel:DWORD src1_sel:BYTE_0
	s_add_u32 s6, s4, s6
	v_bfe_i32 v3, v3, 0, 16
	s_addc_u32 s7, s5, s2
	s_add_i32 s2, s0, 0
	v_add_lshl_u32 v166, v4, v3, 1
	v_lshrrev_b32_e32 v246, 7, v0
	v_and_b32_e32 v247, 15, v0
	v_lshl_or_b32 v246, v246, 4, v247
	v_lshlrev_b32_e32 v246, 4, v246
	v_bfe_u32 v247, v0, 6, 1
	v_bfe_u32 v248, v0, 4, 2
	v_lshl_or_b32 v247, v247, 2, v248
	v_lshl_or_b32 v246, v247, 18, v246
	v_add_u32_e32 v248, 0x400, v246
	v_mov_b32_e32 v244, 0x200000
	v_mov_b32_e32 v245, 0
	v_mov_b32_e32 v247, 0
	v_mov_b32_e32 v249, 0
	s_add_i32 m0, s2, 0x10000
	s_mul_i32 s8, s60, s8
	global_load_lds_dwordx4 v166, s[6:7]
	s_add_i32 m0, s2, 0x12000
	s_add_u32 s12, s6, s58
	global_load_lds_dwordx4 v130, s[6:7]
	s_addc_u32 s13, s7, s59
	s_add_i32 m0, s2, 0x14000
	s_nop 0
	global_load_lds_dwordx4 v166, s[12:13]
	s_add_i32 m0, s2, 0x16000
	s_add_u32 s8, s44, s8
	s_addc_u32 s9, s45, s3
	v_readlane_b32 s8, v254, 25
	s_lshl_b32 s8, s8, 12
	s_add_u32 s8, s44, s8
	s_addc_u32 s9, s45, 0
	s_add_i32 s3, s2, 0x2000
	global_load_lds_dwordx4 v130, s[12:13]
	s_mov_b32 m0, s2
	s_add_u32 s18, s8, 0x800
	global_load_lds_dwordx4 v246, s[8:9]
	s_mov_b32 m0, s3
	s_addc_u32 s19, s9, 0
	s_add_i32 s14, s2, 0x4000
	global_load_lds_dwordx4 v248, s[8:9]
	s_mov_b32 m0, s14
	s_add_i32 s15, s2, 0x6000
	global_load_lds_dwordx4 v246, s[18:19]
	s_mov_b32 m0, s15
	s_cmp_eq_u32 s17, 1
	global_load_lds_dwordx4 v248, s[18:19]
	s_cselect_b64 s[72:73], -1, 0
	s_cmp_lg_u32 s17, 1
	s_cbranch_scc1 .LBB0_737
	s_barrier
.LBB0_737:
	v_bfe_u32 v16, v2, 4, 2
	s_lshr_b32 s11, s11, 26
	v_mov_b32_e32 v131, v167
	v_and_b32_e32 v228, 15, v2
	s_add_i32 s11, s10, s11
	v_lshlrev_b32_e32 v3, 4, v16
	v_lshlrev_b32_e32 v2, 2, v2
	v_lshl_add_u64 v[8:9], s[12:13], 0, v[166:167]
	v_lshl_add_u64 v[10:11], s[12:13], 0, v[130:131]
	s_and_b32 s12, s16, 3
	s_ashr_i32 s13, s11, 6
	v_lshl_or_b32 v3, v228, 6, v3
	s_lshl_b32 s11, s17, 13
	v_and_b32_e32 v2, 32, v2
	v_lshl_add_u64 v[4:5], s[6:7], 0, v[166:167]
	v_bitop3_b32 v17, v3, s11, v2 bitop3:0xde
	s_lshl_b32 s11, s12, 12
	v_lshl_add_u64 v[6:7], s[6:7], 0, v[130:131]
	v_bitop3_b32 v229, v3, s11, v2 bitop3:0xde
	s_add_i32 m0, s2, 0x18000
	v_lshl_add_u64 v[2:3], v[4:5], 0, s[62:63]
	v_lshl_add_u64 v[12:13], s[8:9], 0, v[246:247]
	s_lshl_b32 s16, s17, 6
	s_waitcnt vmcnt(2)
	s_barrier
	global_load_lds_dwordx4 v[2:3], off
	v_lshl_add_u64 v[2:3], v[6:7], 0, s[62:63]
	s_add_i32 m0, s2, 0x1a000
	s_add_i32 s17, s2, 0x8000
	v_lshl_add_u64 v[14:15], s[8:9], 0, v[248:249]
	global_load_lds_dwordx4 v[2:3], off
	v_lshl_add_u64 v[2:3], v[12:13], 0, v[244:245]
	s_mov_b32 m0, s17
	s_add_i32 s18, s2, 0xa000
	global_load_lds_dwordx4 v[2:3], off
	v_lshl_add_u64 v[2:3], v[14:15], 0, v[244:245]
	s_mov_b32 m0, s18
	v_cmp_eq_u32_e64 s[38:39], 0, v16
	global_load_lds_dwordx4 v[2:3], off
	s_add_i32 m0, s2, 0x1c000
	v_lshl_add_u64 v[2:3], v[8:9], 0, s[62:63]
	global_load_lds_dwordx4 v[2:3], off
	v_lshl_add_u64 v[2:3], v[10:11], 0, s[62:63]
	s_add_i32 m0, s2, 0x1e000
	s_cmp_gt_i32 s10, 63
	global_load_lds_dwordx4 v[2:3], off
	s_waitcnt vmcnt(6)
	s_cselect_b64 s[86:87], -1, 0
	s_add_i32 s19, s13, -2
	s_cmpk_lt_u32 s20, 0x100
	v_lshlrev_b32_e32 v2, 2, v16
	v_readlane_b32 s10, v254, 25
	s_cselect_b64 s[88:89], -1, 0
	v_lshl_or_b32 v230, s12, 5, v2
	s_mov_b32 s20, 0
	v_add_u32_e32 v132, 0x800, v248
	v_mov_b32_e32 v133, 0
	v_add_u32_e32 v134, 0x800, v246
	v_mov_b32_e32 v135, 0
	v_add_u32_e32 v231, 0, v17
	v_lshlrev_b32_e32 v231, 4, v228
	v_lshl_or_b32 v231, v16, 8, v231
	s_lshl_b32 s11, s16, 7
	v_or_b32_e32 v231, s11, v231
	v_readlane_b32 s23, v254, 13
	s_mov_b32 s24, s10
	s_barrier
	v_readlane_b32 s11, v254, 26
	s_branch .LBB0_740

; #define PG8_STAGE(bufoff, gbase, voff) do { _Pragma("unroll") for (int _i = 0; _i < 2; ++_i) \
;         __builtin_amdgcn_global_load_lds((const unsigned*)((const char*)(gbase) + (voff)[_i]), (PG8_LAS unsigned*)(lds + (bufoff) + ldsw + _i * 8192), 16, 0, 0); } while (0)
; #define PG8_LDA(dst, b, h) do { _Pragma("unroll") for (int m = 0; m < 4; ++m) _Pragma("unroll") for (int k = 0; k < 2; ++k) dst[m][k] = *(const PG8_LAS bf16x8*)(lds + PG8_SA(b, h) + aoff + m * 2048 + k * 1024); } while (0)
; #define PG8_LDB(dst, b, h) do { _Pragma("unroll") for (int n = 0; n < 2; ++n) _Pragma("unroll") for (int k = 0; k < 2; ++k) dst[n][k] = *(const PG8_LAS bf16x8*)(lds + PG8_SB(b, h) + boff + n * 2048 + k * 1024); } while (0)
; #define PG8_MMA(ai, bj, At, Bt) do { __builtin_amdgcn_s_setprio(1); _Pragma("unroll") for (int m = 0; m < 4; ++m) _Pragma("unroll") for (int n = 0; n < 2; ++n) _Pragma("unroll") for (int k = 0; k < 2; ++k) \
;         acc[ai][bj][m][n] = __builtin_amdgcn_mfma_f32_16x16x32_bf16(Bt[n][k], At[m][k], acc[ai][bj][m][n], 0, 0, 0); __builtin_amdgcn_s_setprio(0); } while (0)
; #define PG8_WAIT_V(n) asm volatile("s_waitcnt vmcnt(" #n ")" ::: "memory")
;     ...
;         const bool has_next = S.next(ui + 1, nxt);
;         const char* nA = has_next ? (const char*)gA + (size_t)nxt.pm * tstepA + (size_t)nxt.pn * acolB : cA; const char* nB = has_next ? (const char*)gB + (size_t)nxt.pn * tstepB : cB;
;         for (int t = 0; t < nt; t += 2) {
;             const bool last = (t == nt - 2);
;             const char* a1 = cA + (size_t)(t + 1) * kstep;
;             const char* a2 = last ? nA : cA + (size_t)(t + 2) * kstep; const char* b2 = last ? nB : cB + (size_t)(t + 2) * kstep;
;             const char* a3 = a2 + kstep; const char* b3 = b2 + kstep;
;             if (last && has_next) S.a_ready(nxt);
;             if constexpr (SP2) {
;             PG8_LDB(B0, 0, 0); PG8_LDB(B1, 0, 1); PG8_SCHED; PG8_LDA(At, 0, 0); PG8_STAGE(PG8_SA(1, 1), a1 + hstepA, voffA);
;             PG8_WAIT_V(8); PG8_WAIT_L(0); PG8_BAR; PG8_MMA(0, 0, At, B0); PG8_MMA(0, 1, At, B1); PG8_BAR; PG8_SCHED;
;             PG8_LDA(At, 0, 1); PG8_STAGE(PG8_SB(0, 0), b2, voffB); PG8_STAGE(PG8_SB(0, 1), b2 + hstepB, voffB); PG8_STAGE(PG8_SA(0, 0), a2, voffA);
;             PG8_WAIT_V(8); PG8_WAIT_L(0); PG8_BAR; PG8_MMA(1, 0, At, B0); PG8_MMA(1, 1, At, B1); PG8_BAR; PG8_SCHED;
.LBB0_750:
	s_andn2_b64 vcc, exec, s[86:87]
	s_waitcnt lgkmcnt(0)
	s_cbranch_vccnz .LBB0_753
	s_add_u32 s10, s6, 0x100
	s_addc_u32 s11, s7, 0
	s_add_u32 s6, s8, 0x200000
	s_addc_u32 s7, s9, 0
	s_mov_b32 s8, 0
	s_add_i32 s25, s8, 2
	s_add_u32 s27, s6, 0x200000
	s_addc_u32 s9, s7, 0
	s_add_i32 s31, 0, 0x10000
	s_cmp_eq_u32 s19, s8
	s_cselect_b32 s9, s43, s9
	s_cselect_b32 s8, s42, s27
	s_cselect_b32 s35, s91, s11
	s_cselect_b32 s34, s90, s10
	s_add_i32 s27, 0, 0x14000
	v_add_u32_e32 v148, s31, v229
	v_add_u32_e32 v164, s27, v229
	ds_read_b128 v[136:139], v148
	ds_read_b128 v[140:143], v148 offset:1024
	ds_read_b128 v[144:147], v148 offset:2048
	ds_read_b128 v[148:151], v148 offset:3072
	ds_read_b128 v[152:155], v164
	ds_read_b128 v[156:159], v164 offset:1024
	ds_read_b128 v[160:163], v164 offset:2048
	ds_read_b128 v[172:175], v164 offset:3072
	v_lshl_add_u64 v[164:165], s[6:7], 0, v[134:135]
	s_add_i32 m0, s2, 0xc000
	ds_read_b128 v[176:179], v231
	ds_read_b128 v[180:183], v231 offset:1024
	ds_read_b128 v[184:187], v231 offset:2048
	ds_read_b128 v[188:191], v231 offset:3072
	ds_read_b128 v[192:195], v231 offset:4096
	ds_read_b128 v[196:199], v231 offset:5120
	ds_read_b128 v[200:203], v231 offset:6144
	ds_read_b128 v[204:207], v231 offset:7168
	global_load_lds_dwordx4 v[164:165], off
	v_lshl_add_u64 v[164:165], s[6:7], 0, v[132:133]
	s_add_i32 m0, s2, 0xe000
	s_nop 0
	global_load_lds_dwordx4 v[164:165], off
	s_waitcnt vmcnt(8)
	s_waitcnt lgkmcnt(0)
	s_barrier
	s_waitcnt lgkmcnt(0)
	v_mfma_f32_16x16x32_bf16 v[126:129], v[136:139], v[176:179], 0
	v_mfma_f32_16x16x32_bf16 v[122:125], v[144:147], v[176:179], 0
	v_mfma_f32_16x16x32_bf16 v[110:113], v[136:139], v[184:187], 0
	v_mfma_f32_16x16x32_bf16 v[106:109], v[144:147], v[184:187], 0
	v_mfma_f32_16x16x32_bf16 v[94:97], v[136:139], v[192:195], 0
	v_mfma_f32_16x16x32_bf16 v[90:93], v[144:147], v[192:195], 0
	v_mfma_f32_16x16x32_bf16 v[78:81], v[136:139], v[200:203], 0
	v_mfma_f32_16x16x32_bf16 v[74:77], v[144:147], v[200:203], 0
	v_mfma_f32_16x16x32_bf16 v[126:129], v[140:143], v[180:183], v[126:129]
	v_mfma_f32_16x16x32_bf16 v[122:125], v[148:151], v[180:183], v[122:125]
	v_mfma_f32_16x16x32_bf16 v[110:113], v[140:143], v[188:191], v[110:113]
	v_mfma_f32_16x16x32_bf16 v[106:109], v[148:151], v[188:191], v[106:109]
	v_mfma_f32_16x16x32_bf16 v[94:97], v[140:143], v[196:199], v[94:97]
	v_mfma_f32_16x16x32_bf16 v[90:93], v[148:151], v[196:199], v[90:93]
	v_mfma_f32_16x16x32_bf16 v[78:81], v[140:143], v[204:207], v[78:81]
	v_mfma_f32_16x16x32_bf16 v[74:77], v[148:151], v[204:207], v[74:77]
	v_mfma_f32_16x16x32_bf16 v[118:121], v[152:155], v[176:179], 0
	v_mfma_f32_16x16x32_bf16 v[114:117], v[160:163], v[176:179], 0
	v_mfma_f32_16x16x32_bf16 v[102:105], v[152:155], v[184:187], 0
	v_mfma_f32_16x16x32_bf16 v[98:101], v[160:163], v[184:187], 0
	v_mfma_f32_16x16x32_bf16 v[86:89], v[152:155], v[192:195], 0
	v_mfma_f32_16x16x32_bf16 v[82:85], v[160:163], v[192:195], 0
	v_mfma_f32_16x16x32_bf16 v[70:73], v[152:155], v[200:203], 0
	v_mfma_f32_16x16x32_bf16 v[66:69], v[160:163], v[200:203], 0
	v_mfma_f32_16x16x32_bf16 v[118:121], v[156:159], v[180:183], v[118:121]
	v_mfma_f32_16x16x32_bf16 v[114:117], v[172:175], v[180:183], v[114:117]
	v_mfma_f32_16x16x32_bf16 v[102:105], v[156:159], v[188:191], v[102:105]
	v_mfma_f32_16x16x32_bf16 v[98:101], v[172:175], v[188:191], v[98:101]
	v_mfma_f32_16x16x32_bf16 v[86:89], v[156:159], v[196:199], v[86:89]
	v_mfma_f32_16x16x32_bf16 v[82:85], v[172:175], v[196:199], v[82:85]
	v_mfma_f32_16x16x32_bf16 v[70:73], v[156:159], v[204:207], v[70:73]
	v_mfma_f32_16x16x32_bf16 v[66:69], v[172:175], v[204:207], v[66:69]
	s_barrier
	s_add_i32 s31, s31, s0
	v_lshl_add_u64 v[164:165], s[34:35], 0, v[166:167]
	s_mov_b32 m0, s31
	ds_read_b128 v[176:179], v231 offset:16384
	ds_read_b128 v[180:183], v231 offset:17408
	ds_read_b128 v[184:187], v231 offset:18432
	ds_read_b128 v[188:191], v231 offset:19456
	ds_read_b128 v[192:195], v231 offset:20480
	ds_read_b128 v[196:199], v231 offset:21504
	ds_read_b128 v[200:203], v231 offset:22528
	ds_read_b128 v[204:207], v231 offset:23552
	global_load_lds_dwordx4 v[164:165], off
	s_add_i32 m0, s31, 0x2000
	v_lshl_add_u64 v[168:169], s[34:35], 0, v[130:131]
	s_add_u32 s34, s34, s58
	s_addc_u32 s35, s35, s59
	s_add_i32 s27, s27, s0
	global_load_lds_dwordx4 v[168:169], off
	v_lshl_add_u64 v[170:171], s[34:35], 0, v[166:167]
	s_mov_b32 m0, s27
	v_lshl_add_u64 v[208:209], s[34:35], 0, v[130:131]
	global_load_lds_dwordx4 v[170:171], off
	s_add_i32 m0, s27, 0x2000
	v_lshl_add_u64 v[210:211], s[8:9], 0, v[246:247]
	global_load_lds_dwordx4 v[208:209], off
	s_mov_b32 m0, s2
	v_lshl_add_u64 v[212:213], s[8:9], 0, v[248:249]
	global_load_lds_dwordx4 v[210:211], off
	s_mov_b32 m0, s3
	s_nop 0
	global_load_lds_dwordx4 v[212:213], off
	s_waitcnt vmcnt(8)
	s_waitcnt lgkmcnt(0)
	s_barrier
; #define PG8_STAGE(bufoff, gbase, voff) do { _Pragma("unroll") for (int _i = 0; _i < 2; ++_i) \
;         __builtin_amdgcn_global_load_lds((const unsigned*)((const char*)(gbase) + (voff)[_i]), (PG8_LAS unsigned*)(lds + (bufoff) + ldsw + _i * 8192), 16, 0, 0); } while (0)
; #define PG8_LDA(dst, b, h) do { _Pragma("unroll") for (int m = 0; m < 4; ++m) _Pragma("unroll") for (int k = 0; k < 2; ++k) dst[m][k] = *(const PG8_LAS bf16x8*)(lds + PG8_SA(b, h) + aoff + m * 2048 + k * 1024); } while (0)
; #define PG8_LDB(dst, b, h) do { _Pragma("unroll") for (int n = 0; n < 2; ++n) _Pragma("unroll") for (int k = 0; k < 2; ++k) dst[n][k] = *(const PG8_LAS bf16x8*)(lds + PG8_SB(b, h) + boff + n * 2048 + k * 1024); } while (0)
; #define PG8_MMA(ai, bj, At, Bt) do { __builtin_amdgcn_s_setprio(1); _Pragma("unroll") for (int m = 0; m < 4; ++m) _Pragma("unroll") for (int n = 0; n < 2; ++n) _Pragma("unroll") for (int k = 0; k < 2; ++k) \
;         acc[ai][bj][m][n] = __builtin_amdgcn_mfma_f32_16x16x32_bf16(Bt[n][k], At[m][k], acc[ai][bj][m][n], 0, 0, 0); __builtin_amdgcn_s_setprio(0); } while (0)
; #define PG8_WAIT_V(n) asm volatile("s_waitcnt vmcnt(" #n ")" ::: "memory")
; #define PG8_WAIT_L(n) asm volatile("s_waitcnt lgkmcnt(" #n ")" ::: "memory")
; #define PG8_BAR __builtin_amdgcn_s_barrier()
; #define PG8_SCHED __builtin_amdgcn_sched_barrier(0)
;     ...
;             PG8_WAIT_V(8); PG8_WAIT_L(0); PG8_BAR; PG8_MMA(1, 0, At, B0); PG8_MMA(1, 1, At, B1); PG8_BAR; PG8_SCHED;
;             PG8_LDB(B0, 1, 0); PG8_LDB(B1, 1, 1); PG8_SCHED; PG8_LDA(At, 1, 0); PG8_STAGE(PG8_SA(0, 1), a2 + hstepA, voffA);
;             PG8_WAIT_V(8); PG8_WAIT_L(0); PG8_BAR; PG8_MMA(0, 0, At, B0); PG8_MMA(0, 1, At, B1); PG8_BAR; PG8_SCHED;
	s_waitcnt lgkmcnt(0)
	v_mfma_f32_16x16x32_bf16 v[62:65], v[136:139], v[176:179], 0
	v_mfma_f32_16x16x32_bf16 v[58:61], v[144:147], v[176:179], 0
	v_mfma_f32_16x16x32_bf16 v[46:49], v[136:139], v[184:187], 0
	v_mfma_f32_16x16x32_bf16 v[42:45], v[144:147], v[184:187], 0
	v_mfma_f32_16x16x32_bf16 v[30:33], v[136:139], v[192:195], 0
	v_mfma_f32_16x16x32_bf16 v[26:29], v[144:147], v[192:195], 0
	v_mfma_f32_16x16x32_bf16 v[14:17], v[136:139], v[200:203], 0
	v_mfma_f32_16x16x32_bf16 v[10:13], v[144:147], v[200:203], 0
	v_mfma_f32_16x16x32_bf16 v[62:65], v[140:143], v[180:183], v[62:65]
	v_mfma_f32_16x16x32_bf16 v[58:61], v[148:151], v[180:183], v[58:61]
	v_mfma_f32_16x16x32_bf16 v[46:49], v[140:143], v[188:191], v[46:49]
	v_mfma_f32_16x16x32_bf16 v[42:45], v[148:151], v[188:191], v[42:45]
	v_mfma_f32_16x16x32_bf16 v[30:33], v[140:143], v[196:199], v[30:33]
	v_mfma_f32_16x16x32_bf16 v[26:29], v[148:151], v[196:199], v[26:29]
	v_mfma_f32_16x16x32_bf16 v[14:17], v[140:143], v[204:207], v[14:17]
	v_mfma_f32_16x16x32_bf16 v[10:13], v[148:151], v[204:207], v[10:13]
	v_mfma_f32_16x16x32_bf16 v[54:57], v[152:155], v[176:179], 0
	v_mfma_f32_16x16x32_bf16 v[50:53], v[160:163], v[176:179], 0
	v_mfma_f32_16x16x32_bf16 v[38:41], v[152:155], v[184:187], 0
	v_mfma_f32_16x16x32_bf16 v[34:37], v[160:163], v[184:187], 0
	v_mfma_f32_16x16x32_bf16 v[22:25], v[152:155], v[192:195], 0
	v_mfma_f32_16x16x32_bf16 v[18:21], v[160:163], v[192:195], 0
	v_mfma_f32_16x16x32_bf16 v[6:9], v[152:155], v[200:203], 0
	v_mfma_f32_16x16x32_bf16 v[2:5], v[160:163], v[200:203], 0
	v_mfma_f32_16x16x32_bf16 v[54:57], v[156:159], v[180:183], v[54:57]
	v_mfma_f32_16x16x32_bf16 v[50:53], v[172:175], v[180:183], v[50:53]
	v_mfma_f32_16x16x32_bf16 v[38:41], v[156:159], v[188:191], v[38:41]
	v_mfma_f32_16x16x32_bf16 v[34:37], v[172:175], v[188:191], v[34:37]
	v_mfma_f32_16x16x32_bf16 v[22:25], v[156:159], v[196:199], v[22:25]
	v_mfma_f32_16x16x32_bf16 v[18:21], v[172:175], v[196:199], v[18:21]
	v_mfma_f32_16x16x32_bf16 v[6:9], v[156:159], v[204:207], v[6:9]
	v_mfma_f32_16x16x32_bf16 v[2:5], v[172:175], v[204:207], v[2:5]
	s_barrier
	s_add_i32 s27, 0, 0x18000
	s_add_i32 s31, 0, 0x1c000
	v_add_u32_e32 v148, s27, v229
	v_add_u32_e32 v172, s31, v229
	ds_read_b128 v[136:139], v148
	ds_read_b128 v[140:143], v148 offset:1024
	ds_read_b128 v[144:147], v148 offset:2048
	ds_read_b128 v[148:151], v148 offset:3072
	ds_read_b128 v[152:155], v172
	ds_read_b128 v[156:159], v172 offset:1024
	ds_read_b128 v[160:163], v172 offset:2048
	ds_read_b128 v[172:175], v172 offset:3072
	s_add_u32 s8, s8, 0x800
	s_addc_u32 s9, s9, 0
	s_mov_b32 m0, s14
	v_lshl_add_u64 v[214:215], s[8:9], 0, v[246:247]
	ds_read_b128 v[176:179], v231 offset:32768
	ds_read_b128 v[180:183], v231 offset:33792
	ds_read_b128 v[184:187], v231 offset:34816
	ds_read_b128 v[188:191], v231 offset:35840
	ds_read_b128 v[192:195], v231 offset:36864
	ds_read_b128 v[196:199], v231 offset:37888
	ds_read_b128 v[200:203], v231 offset:38912
	ds_read_b128 v[204:207], v231 offset:39936
	global_load_lds_dwordx4 v[214:215], off
	v_lshl_add_u64 v[214:215], s[8:9], 0, v[248:249]
	s_mov_b32 m0, s15
	s_nop 0
	global_load_lds_dwordx4 v[214:215], off
	s_waitcnt vmcnt(8)
	s_waitcnt lgkmcnt(0)
	s_barrier
	s_waitcnt lgkmcnt(0)
	v_mfma_f32_16x16x32_bf16 v[126:129], v[136:139], v[176:179], v[126:129]
	v_mfma_f32_16x16x32_bf16 v[122:125], v[144:147], v[176:179], v[122:125]
	v_mfma_f32_16x16x32_bf16 v[110:113], v[136:139], v[184:187], v[110:113]
	v_mfma_f32_16x16x32_bf16 v[106:109], v[144:147], v[184:187], v[106:109]
	v_mfma_f32_16x16x32_bf16 v[94:97], v[136:139], v[192:195], v[94:97]
	v_mfma_f32_16x16x32_bf16 v[90:93], v[144:147], v[192:195], v[90:93]
	v_mfma_f32_16x16x32_bf16 v[78:81], v[136:139], v[200:203], v[78:81]
	v_mfma_f32_16x16x32_bf16 v[74:77], v[144:147], v[200:203], v[74:77]
	v_mfma_f32_16x16x32_bf16 v[126:129], v[140:143], v[180:183], v[126:129]
	v_mfma_f32_16x16x32_bf16 v[122:125], v[148:151], v[180:183], v[122:125]
	v_mfma_f32_16x16x32_bf16 v[110:113], v[140:143], v[188:191], v[110:113]
	v_mfma_f32_16x16x32_bf16 v[106:109], v[148:151], v[188:191], v[106:109]
	v_mfma_f32_16x16x32_bf16 v[94:97], v[140:143], v[196:199], v[94:97]
	v_mfma_f32_16x16x32_bf16 v[90:93], v[148:151], v[196:199], v[90:93]
	v_mfma_f32_16x16x32_bf16 v[78:81], v[140:143], v[204:207], v[78:81]
	v_mfma_f32_16x16x32_bf16 v[74:77], v[148:151], v[204:207], v[74:77]
	v_mfma_f32_16x16x32_bf16 v[118:121], v[152:155], v[176:179], v[118:121]
	v_mfma_f32_16x16x32_bf16 v[114:117], v[160:163], v[176:179], v[114:117]
	v_mfma_f32_16x16x32_bf16 v[102:105], v[152:155], v[184:187], v[102:105]
	v_mfma_f32_16x16x32_bf16 v[98:101], v[160:163], v[184:187], v[98:101]
	v_mfma_f32_16x16x32_bf16 v[86:89], v[152:155], v[192:195], v[86:89]
	v_mfma_f32_16x16x32_bf16 v[82:85], v[160:163], v[192:195], v[82:85]
	v_mfma_f32_16x16x32_bf16 v[70:73], v[152:155], v[200:203], v[70:73]
	v_mfma_f32_16x16x32_bf16 v[66:69], v[160:163], v[200:203], v[66:69]
	v_mfma_f32_16x16x32_bf16 v[118:121], v[156:159], v[180:183], v[118:121]
	v_mfma_f32_16x16x32_bf16 v[114:117], v[172:175], v[180:183], v[114:117]
	v_mfma_f32_16x16x32_bf16 v[102:105], v[156:159], v[188:191], v[102:105]
	v_mfma_f32_16x16x32_bf16 v[98:101], v[172:175], v[188:191], v[98:101]
	v_mfma_f32_16x16x32_bf16 v[86:89], v[156:159], v[196:199], v[86:89]
	v_mfma_f32_16x16x32_bf16 v[82:85], v[172:175], v[196:199], v[82:85]
	v_mfma_f32_16x16x32_bf16 v[70:73], v[156:159], v[204:207], v[70:73]
	v_mfma_f32_16x16x32_bf16 v[66:69], v[172:175], v[204:207], v[66:69]
	s_barrier
; #define PG8_STAGE(bufoff, gbase, voff) do { _Pragma("unroll") for (int _i = 0; _i < 2; ++_i) \
;         __builtin_amdgcn_global_load_lds((const unsigned*)((const char*)(gbase) + (voff)[_i]), (PG8_LAS unsigned*)(lds + (bufoff) + ldsw + _i * 8192), 16, 0, 0); } while (0)
; #define PG8_LDA(dst, b, h) do { _Pragma("unroll") for (int m = 0; m < 4; ++m) _Pragma("unroll") for (int k = 0; k < 2; ++k) dst[m][k] = *(const PG8_LAS bf16x8*)(lds + PG8_SA(b, h) + aoff + m * 2048 + k * 1024); } while (0)
; #define PG8_LDB(dst, b, h) do { _Pragma("unroll") for (int n = 0; n < 2; ++n) _Pragma("unroll") for (int k = 0; k < 2; ++k) dst[n][k] = *(const PG8_LAS bf16x8*)(lds + PG8_SB(b, h) + boff + n * 2048 + k * 1024); } while (0)
; #define PG8_WAIT_V(n) asm volatile("s_waitcnt vmcnt(" #n ")" ::: "memory")
; #define PG8_WAIT_L(n) asm volatile("s_waitcnt lgkmcnt(" #n ")" ::: "memory")
; #define PG8_BAR __builtin_amdgcn_s_barrier()
;     ...
;         for (int t = 0; t < nt; t += 2) {
;             const bool last = (t == nt - 2);
;             const char* a1 = cA + (size_t)(t + 1) * kstep;
;             const char* a2 = last ? nA : cA + (size_t)(t + 2) * kstep; const char* b2 = last ? nB : cB + (size_t)(t + 2) * kstep;
;             const char* a3 = a2 + kstep; const char* b3 = b2 + kstep;
;             if (last && has_next) S.a_ready(nxt);
;             if constexpr (SP2) {
;             PG8_LDB(B0, 0, 0); PG8_LDB(B1, 0, 1); PG8_SCHED; PG8_LDA(At, 0, 0); PG8_STAGE(PG8_SA(1, 1), a1 + hstepA, voffA);
;             PG8_WAIT_V(8); PG8_WAIT_L(0); PG8_BAR; PG8_MMA(0, 0, At, B0); PG8_MMA(0, 1, At, B1); PG8_BAR; PG8_SCHED;
;             PG8_LDA(At, 0, 1); PG8_STAGE(PG8_SB(0, 0), b2, voffB); PG8_STAGE(PG8_SB(0, 1), b2 + hstepB, voffB); PG8_STAGE(PG8_SA(0, 0), a2, voffA);
;             PG8_WAIT_V(8); PG8_WAIT_L(0); PG8_BAR; PG8_MMA(1, 0, At, B0); PG8_MMA(1, 1, At, B1); PG8_BAR; PG8_SCHED;
;             PG8_LDB(B0, 1, 0); PG8_LDB(B1, 1, 1); PG8_SCHED; PG8_LDA(At, 1, 0); PG8_STAGE(PG8_SA(0, 1), a2 + hstepA, voffA);
;             PG8_WAIT_V(8); PG8_WAIT_L(0); PG8_BAR; PG8_MMA(0, 0, At, B0); PG8_MMA(0, 1, At, B1); PG8_BAR; PG8_SCHED;
;             PG8_LDA(At, 1, 1); PG8_STAGE(PG8_SB(1, 0), b3, voffB); PG8_STAGE(PG8_SB(1, 1), b3 + hstepB, voffB); PG8_STAGE(PG8_SA(1, 0), a3, voffA);
;             PG8_WAIT_V(8); PG8_WAIT_L(0); PG8_BAR; PG8_MMA(1, 0, At, B0); PG8_MMA(1, 1, At, B1); PG8_BAR; PG8_SCHED;
	s_add_i32 s8, s27, s0
	v_lshl_add_u64 v[164:165], v[164:165], 0, s[62:63]
	s_mov_b32 m0, s8
	ds_read_b128 v[176:179], v231 offset:49152
	ds_read_b128 v[180:183], v231 offset:50176
	ds_read_b128 v[184:187], v231 offset:51200
	ds_read_b128 v[188:191], v231 offset:52224
	ds_read_b128 v[192:195], v231 offset:53248
	ds_read_b128 v[196:199], v231 offset:54272
	ds_read_b128 v[200:203], v231 offset:55296
	ds_read_b128 v[204:207], v231 offset:56320
	global_load_lds_dwordx4 v[164:165], off
	v_lshl_add_u64 v[164:165], v[168:169], 0, s[62:63]
	s_add_i32 m0, s8, 0x2000
	s_add_i32 s8, s31, s0
	global_load_lds_dwordx4 v[164:165], off
	v_lshl_add_u64 v[164:165], v[170:171], 0, s[62:63]
	s_mov_b32 m0, s8
	s_nop 0
	global_load_lds_dwordx4 v[164:165], off
	v_lshl_add_u64 v[164:165], v[208:209], 0, s[62:63]
	s_add_i32 m0, s8, 0x2000
	s_nop 0
	global_load_lds_dwordx4 v[164:165], off
	v_lshl_add_u64 v[164:165], v[210:211], 0, v[244:245]
	s_mov_b32 m0, s17
	s_nop 0
	global_load_lds_dwordx4 v[164:165], off
	v_lshl_add_u64 v[164:165], v[212:213], 0, v[244:245]
	s_mov_b32 m0, s18
	s_nop 0
	global_load_lds_dwordx4 v[164:165], off
	s_waitcnt vmcnt(8)
	s_waitcnt lgkmcnt(0)
	s_barrier
	s_waitcnt lgkmcnt(0)
	v_mfma_f32_16x16x32_bf16 v[62:65], v[136:139], v[176:179], v[62:65]
	v_mfma_f32_16x16x32_bf16 v[58:61], v[144:147], v[176:179], v[58:61]
	v_mfma_f32_16x16x32_bf16 v[46:49], v[136:139], v[184:187], v[46:49]
	v_mfma_f32_16x16x32_bf16 v[42:45], v[144:147], v[184:187], v[42:45]
	v_mfma_f32_16x16x32_bf16 v[30:33], v[136:139], v[192:195], v[30:33]
	v_mfma_f32_16x16x32_bf16 v[26:29], v[144:147], v[192:195], v[26:29]
	v_mfma_f32_16x16x32_bf16 v[14:17], v[136:139], v[200:203], v[14:17]
	v_mfma_f32_16x16x32_bf16 v[10:13], v[144:147], v[200:203], v[10:13]
	v_mfma_f32_16x16x32_bf16 v[62:65], v[140:143], v[180:183], v[62:65]
	v_mfma_f32_16x16x32_bf16 v[58:61], v[148:151], v[180:183], v[58:61]
	v_mfma_f32_16x16x32_bf16 v[46:49], v[140:143], v[188:191], v[46:49]
	v_mfma_f32_16x16x32_bf16 v[42:45], v[148:151], v[188:191], v[42:45]
	v_mfma_f32_16x16x32_bf16 v[30:33], v[140:143], v[196:199], v[30:33]
	v_mfma_f32_16x16x32_bf16 v[26:29], v[148:151], v[196:199], v[26:29]
	v_mfma_f32_16x16x32_bf16 v[14:17], v[140:143], v[204:207], v[14:17]
	v_mfma_f32_16x16x32_bf16 v[10:13], v[148:151], v[204:207], v[10:13]
	v_mfma_f32_16x16x32_bf16 v[54:57], v[152:155], v[176:179], v[54:57]
	v_mfma_f32_16x16x32_bf16 v[50:53], v[160:163], v[176:179], v[50:53]
	v_mfma_f32_16x16x32_bf16 v[38:41], v[152:155], v[184:187], v[38:41]
	v_mfma_f32_16x16x32_bf16 v[34:37], v[160:163], v[184:187], v[34:37]
	v_mfma_f32_16x16x32_bf16 v[22:25], v[152:155], v[192:195], v[22:25]
	v_mfma_f32_16x16x32_bf16 v[18:21], v[160:163], v[192:195], v[18:21]
	v_mfma_f32_16x16x32_bf16 v[6:9], v[152:155], v[200:203], v[6:9]
	v_mfma_f32_16x16x32_bf16 v[2:5], v[160:163], v[200:203], v[2:5]
	v_mfma_f32_16x16x32_bf16 v[54:57], v[156:159], v[180:183], v[54:57]
	v_mfma_f32_16x16x32_bf16 v[50:53], v[172:175], v[180:183], v[50:53]
	v_mfma_f32_16x16x32_bf16 v[38:41], v[156:159], v[188:191], v[38:41]
	v_mfma_f32_16x16x32_bf16 v[34:37], v[172:175], v[188:191], v[34:37]
	v_mfma_f32_16x16x32_bf16 v[22:25], v[156:159], v[196:199], v[22:25]
	v_mfma_f32_16x16x32_bf16 v[18:21], v[172:175], v[196:199], v[18:21]
	v_mfma_f32_16x16x32_bf16 v[6:9], v[156:159], v[204:207], v[6:9]
	v_mfma_f32_16x16x32_bf16 v[2:5], v[172:175], v[204:207], v[2:5]
	s_barrier
	s_add_u32 s10, s10, 0x100
	s_addc_u32 s11, s11, 0
	s_add_u32 s6, s6, 0x400000
	s_addc_u32 s7, s7, 0
	s_cmp_ge_i32 s25, s13
	s_mov_b32 s8, s25
	s_cbranch_scc1 .LBB0_753
.LBB0_752:
	s_add_i32 s25, s8, 2
	s_add_u32 s27, s6, 0x200000
	s_addc_u32 s9, s7, 0
	s_add_i32 s31, 0, 0x10000
	s_cmp_eq_u32 s19, s8
	s_cselect_b32 s9, s43, s9
	s_cselect_b32 s8, s42, s27
	s_cselect_b32 s35, s91, s11
	s_cselect_b32 s34, s90, s10
	s_add_i32 s27, 0, 0x14000
	v_add_u32_e32 v148, s31, v229
	v_add_u32_e32 v164, s27, v229
	ds_read_b128 v[136:139], v148
	ds_read_b128 v[140:143], v148 offset:1024
	ds_read_b128 v[144:147], v148 offset:2048
	ds_read_b128 v[148:151], v148 offset:3072
	ds_read_b128 v[152:155], v164
	ds_read_b128 v[156:159], v164 offset:1024
	ds_read_b128 v[160:163], v164 offset:2048
	ds_read_b128 v[172:175], v164 offset:3072
	v_lshl_add_u64 v[164:165], s[6:7], 0, v[134:135]
	s_add_i32 m0, s2, 0xc000
	ds_read_b128 v[176:179], v231
	ds_read_b128 v[180:183], v231 offset:1024
	ds_read_b128 v[184:187], v231 offset:2048
	ds_read_b128 v[188:191], v231 offset:3072
	ds_read_b128 v[192:195], v231 offset:4096
	ds_read_b128 v[196:199], v231 offset:5120
	ds_read_b128 v[200:203], v231 offset:6144
	ds_read_b128 v[204:207], v231 offset:7168
	global_load_lds_dwordx4 v[164:165], off
	v_lshl_add_u64 v[164:165], s[6:7], 0, v[132:133]
	s_add_i32 m0, s2, 0xe000
	s_nop 0
	global_load_lds_dwordx4 v[164:165], off
	s_waitcnt vmcnt(8)
	s_waitcnt lgkmcnt(0)
	s_barrier
; #define PG8_STAGE(bufoff, gbase, voff) do { _Pragma("unroll") for (int _i = 0; _i < 2; ++_i) \
;         __builtin_amdgcn_global_load_lds((const unsigned*)((const char*)(gbase) + (voff)[_i]), (PG8_LAS unsigned*)(lds + (bufoff) + ldsw + _i * 8192), 16, 0, 0); } while (0)
; #define PG8_LDA(dst, b, h) do { _Pragma("unroll") for (int m = 0; m < 4; ++m) _Pragma("unroll") for (int k = 0; k < 2; ++k) dst[m][k] = *(const PG8_LAS bf16x8*)(lds + PG8_SA(b, h) + aoff + m * 2048 + k * 1024); } while (0)
; #define PG8_LDB(dst, b, h) do { _Pragma("unroll") for (int n = 0; n < 2; ++n) _Pragma("unroll") for (int k = 0; k < 2; ++k) dst[n][k] = *(const PG8_LAS bf16x8*)(lds + PG8_SB(b, h) + boff + n * 2048 + k * 1024); } while (0)
; #define PG8_MMA(ai, bj, At, Bt) do { __builtin_amdgcn_s_setprio(1); _Pragma("unroll") for (int m = 0; m < 4; ++m) _Pragma("unroll") for (int n = 0; n < 2; ++n) _Pragma("unroll") for (int k = 0; k < 2; ++k) \
;         acc[ai][bj][m][n] = __builtin_amdgcn_mfma_f32_16x16x32_bf16(Bt[n][k], At[m][k], acc[ai][bj][m][n], 0, 0, 0); __builtin_amdgcn_s_setprio(0); } while (0)
; #define PG8_WAIT_V(n) asm volatile("s_waitcnt vmcnt(" #n ")" ::: "memory")
; #define PG8_WAIT_L(n) asm volatile("s_waitcnt lgkmcnt(" #n ")" ::: "memory")
; #define PG8_BAR __builtin_amdgcn_s_barrier()
; #define PG8_SCHED __builtin_amdgcn_sched_barrier(0)
;     ...
;             PG8_LDB(B0, 0, 0); PG8_LDB(B1, 0, 1); PG8_SCHED; PG8_LDA(At, 0, 0); PG8_STAGE(PG8_SA(1, 1), a1 + hstepA, voffA);
;             PG8_WAIT_V(8); PG8_WAIT_L(0); PG8_BAR; PG8_MMA(0, 0, At, B0); PG8_MMA(0, 1, At, B1); PG8_BAR; PG8_SCHED;
;             PG8_LDA(At, 0, 1); PG8_STAGE(PG8_SB(0, 0), b2, voffB); PG8_STAGE(PG8_SB(0, 1), b2 + hstepB, voffB); PG8_STAGE(PG8_SA(0, 0), a2, voffA);
;             PG8_WAIT_V(8); PG8_WAIT_L(0); PG8_BAR; PG8_MMA(1, 0, At, B0); PG8_MMA(1, 1, At, B1); PG8_BAR; PG8_SCHED;
	s_waitcnt lgkmcnt(0)
	v_mfma_f32_16x16x32_bf16 v[126:129], v[136:139], v[176:179], v[126:129]
	v_mfma_f32_16x16x32_bf16 v[122:125], v[144:147], v[176:179], v[122:125]
	v_mfma_f32_16x16x32_bf16 v[110:113], v[136:139], v[184:187], v[110:113]
	v_mfma_f32_16x16x32_bf16 v[106:109], v[144:147], v[184:187], v[106:109]
	v_mfma_f32_16x16x32_bf16 v[94:97], v[136:139], v[192:195], v[94:97]
	v_mfma_f32_16x16x32_bf16 v[90:93], v[144:147], v[192:195], v[90:93]
	v_mfma_f32_16x16x32_bf16 v[78:81], v[136:139], v[200:203], v[78:81]
	v_mfma_f32_16x16x32_bf16 v[74:77], v[144:147], v[200:203], v[74:77]
	v_mfma_f32_16x16x32_bf16 v[126:129], v[140:143], v[180:183], v[126:129]
	v_mfma_f32_16x16x32_bf16 v[122:125], v[148:151], v[180:183], v[122:125]
	v_mfma_f32_16x16x32_bf16 v[110:113], v[140:143], v[188:191], v[110:113]
	v_mfma_f32_16x16x32_bf16 v[106:109], v[148:151], v[188:191], v[106:109]
	v_mfma_f32_16x16x32_bf16 v[94:97], v[140:143], v[196:199], v[94:97]
	v_mfma_f32_16x16x32_bf16 v[90:93], v[148:151], v[196:199], v[90:93]
	v_mfma_f32_16x16x32_bf16 v[78:81], v[140:143], v[204:207], v[78:81]
	v_mfma_f32_16x16x32_bf16 v[74:77], v[148:151], v[204:207], v[74:77]
	v_mfma_f32_16x16x32_bf16 v[118:121], v[152:155], v[176:179], v[118:121]
	v_mfma_f32_16x16x32_bf16 v[114:117], v[160:163], v[176:179], v[114:117]
	v_mfma_f32_16x16x32_bf16 v[102:105], v[152:155], v[184:187], v[102:105]
	v_mfma_f32_16x16x32_bf16 v[98:101], v[160:163], v[184:187], v[98:101]
	v_mfma_f32_16x16x32_bf16 v[86:89], v[152:155], v[192:195], v[86:89]
	v_mfma_f32_16x16x32_bf16 v[82:85], v[160:163], v[192:195], v[82:85]
	v_mfma_f32_16x16x32_bf16 v[70:73], v[152:155], v[200:203], v[70:73]
	v_mfma_f32_16x16x32_bf16 v[66:69], v[160:163], v[200:203], v[66:69]
	v_mfma_f32_16x16x32_bf16 v[118:121], v[156:159], v[180:183], v[118:121]
	v_mfma_f32_16x16x32_bf16 v[114:117], v[172:175], v[180:183], v[114:117]
	v_mfma_f32_16x16x32_bf16 v[102:105], v[156:159], v[188:191], v[102:105]
	v_mfma_f32_16x16x32_bf16 v[98:101], v[172:175], v[188:191], v[98:101]
	v_mfma_f32_16x16x32_bf16 v[86:89], v[156:159], v[196:199], v[86:89]
	v_mfma_f32_16x16x32_bf16 v[82:85], v[172:175], v[196:199], v[82:85]
	v_mfma_f32_16x16x32_bf16 v[70:73], v[156:159], v[204:207], v[70:73]
	v_mfma_f32_16x16x32_bf16 v[66:69], v[172:175], v[204:207], v[66:69]
	s_barrier
	s_add_i32 s31, s31, s0
	v_lshl_add_u64 v[164:165], s[34:35], 0, v[166:167]
	s_mov_b32 m0, s31
	ds_read_b128 v[176:179], v231 offset:16384
	ds_read_b128 v[180:183], v231 offset:17408
	ds_read_b128 v[184:187], v231 offset:18432
	ds_read_b128 v[188:191], v231 offset:19456
	ds_read_b128 v[192:195], v231 offset:20480
	ds_read_b128 v[196:199], v231 offset:21504
	ds_read_b128 v[200:203], v231 offset:22528
	ds_read_b128 v[204:207], v231 offset:23552
	global_load_lds_dwordx4 v[164:165], off
	s_add_i32 m0, s31, 0x2000
	v_lshl_add_u64 v[168:169], s[34:35], 0, v[130:131]
	s_add_u32 s34, s34, s58
	s_addc_u32 s35, s35, s59
	s_add_i32 s27, s27, s0
	global_load_lds_dwordx4 v[168:169], off
	v_lshl_add_u64 v[170:171], s[34:35], 0, v[166:167]
	s_mov_b32 m0, s27
	v_lshl_add_u64 v[208:209], s[34:35], 0, v[130:131]
	global_load_lds_dwordx4 v[170:171], off
	s_add_i32 m0, s27, 0x2000
	v_lshl_add_u64 v[210:211], s[8:9], 0, v[246:247]
	global_load_lds_dwordx4 v[208:209], off
	s_mov_b32 m0, s2
	v_lshl_add_u64 v[212:213], s[8:9], 0, v[248:249]
	global_load_lds_dwordx4 v[210:211], off
	s_mov_b32 m0, s3
	s_nop 0
	global_load_lds_dwordx4 v[212:213], off
	s_waitcnt vmcnt(8)
	s_waitcnt lgkmcnt(0)
	s_barrier
	s_waitcnt lgkmcnt(0)
	v_mfma_f32_16x16x32_bf16 v[62:65], v[136:139], v[176:179], v[62:65]
	v_mfma_f32_16x16x32_bf16 v[58:61], v[144:147], v[176:179], v[58:61]
	v_mfma_f32_16x16x32_bf16 v[46:49], v[136:139], v[184:187], v[46:49]
	v_mfma_f32_16x16x32_bf16 v[42:45], v[144:147], v[184:187], v[42:45]
	v_mfma_f32_16x16x32_bf16 v[30:33], v[136:139], v[192:195], v[30:33]
	v_mfma_f32_16x16x32_bf16 v[26:29], v[144:147], v[192:195], v[26:29]
	v_mfma_f32_16x16x32_bf16 v[14:17], v[136:139], v[200:203], v[14:17]
	v_mfma_f32_16x16x32_bf16 v[10:13], v[144:147], v[200:203], v[10:13]
	v_mfma_f32_16x16x32_bf16 v[62:65], v[140:143], v[180:183], v[62:65]
	v_mfma_f32_16x16x32_bf16 v[58:61], v[148:151], v[180:183], v[58:61]
	v_mfma_f32_16x16x32_bf16 v[46:49], v[140:143], v[188:191], v[46:49]
	v_mfma_f32_16x16x32_bf16 v[42:45], v[148:151], v[188:191], v[42:45]
	v_mfma_f32_16x16x32_bf16 v[30:33], v[140:143], v[196:199], v[30:33]
	v_mfma_f32_16x16x32_bf16 v[26:29], v[148:151], v[196:199], v[26:29]
	v_mfma_f32_16x16x32_bf16 v[14:17], v[140:143], v[204:207], v[14:17]
	v_mfma_f32_16x16x32_bf16 v[10:13], v[148:151], v[204:207], v[10:13]
	v_mfma_f32_16x16x32_bf16 v[54:57], v[152:155], v[176:179], v[54:57]
	v_mfma_f32_16x16x32_bf16 v[50:53], v[160:163], v[176:179], v[50:53]
	v_mfma_f32_16x16x32_bf16 v[38:41], v[152:155], v[184:187], v[38:41]
	v_mfma_f32_16x16x32_bf16 v[34:37], v[160:163], v[184:187], v[34:37]
	v_mfma_f32_16x16x32_bf16 v[22:25], v[152:155], v[192:195], v[22:25]
	v_mfma_f32_16x16x32_bf16 v[18:21], v[160:163], v[192:195], v[18:21]
	v_mfma_f32_16x16x32_bf16 v[6:9], v[152:155], v[200:203], v[6:9]
	v_mfma_f32_16x16x32_bf16 v[2:5], v[160:163], v[200:203], v[2:5]
	v_mfma_f32_16x16x32_bf16 v[54:57], v[156:159], v[180:183], v[54:57]
	v_mfma_f32_16x16x32_bf16 v[50:53], v[172:175], v[180:183], v[50:53]
	v_mfma_f32_16x16x32_bf16 v[38:41], v[156:159], v[188:191], v[38:41]
	v_mfma_f32_16x16x32_bf16 v[34:37], v[172:175], v[188:191], v[34:37]
	v_mfma_f32_16x16x32_bf16 v[22:25], v[156:159], v[196:199], v[22:25]
	v_mfma_f32_16x16x32_bf16 v[18:21], v[172:175], v[196:199], v[18:21]
	v_mfma_f32_16x16x32_bf16 v[6:9], v[156:159], v[204:207], v[6:9]
	v_mfma_f32_16x16x32_bf16 v[2:5], v[172:175], v[204:207], v[2:5]
	s_barrier
; #define PG8_STAGE(bufoff, gbase, voff) do { _Pragma("unroll") for (int _i = 0; _i < 2; ++_i) \
;         __builtin_amdgcn_global_load_lds((const unsigned*)((const char*)(gbase) + (voff)[_i]), (PG8_LAS unsigned*)(lds + (bufoff) + ldsw + _i * 8192), 16, 0, 0); } while (0)
; #define PG8_LDA(dst, b, h) do { _Pragma("unroll") for (int m = 0; m < 4; ++m) _Pragma("unroll") for (int k = 0; k < 2; ++k) dst[m][k] = *(const PG8_LAS bf16x8*)(lds + PG8_SA(b, h) + aoff + m * 2048 + k * 1024); } while (0)
; #define PG8_LDB(dst, b, h) do { _Pragma("unroll") for (int n = 0; n < 2; ++n) _Pragma("unroll") for (int k = 0; k < 2; ++k) dst[n][k] = *(const PG8_LAS bf16x8*)(lds + PG8_SB(b, h) + boff + n * 2048 + k * 1024); } while (0)
; #define PG8_MMA(ai, bj, At, Bt) do { __builtin_amdgcn_s_setprio(1); _Pragma("unroll") for (int m = 0; m < 4; ++m) _Pragma("unroll") for (int n = 0; n < 2; ++n) _Pragma("unroll") for (int k = 0; k < 2; ++k) \
;         acc[ai][bj][m][n] = __builtin_amdgcn_mfma_f32_16x16x32_bf16(Bt[n][k], At[m][k], acc[ai][bj][m][n], 0, 0, 0); __builtin_amdgcn_s_setprio(0); } while (0)
; #define PG8_WAIT_V(n) asm volatile("s_waitcnt vmcnt(" #n ")" ::: "memory")
; #define PG8_WAIT_L(n) asm volatile("s_waitcnt lgkmcnt(" #n ")" ::: "memory")
; #define PG8_BAR __builtin_amdgcn_s_barrier()
; #define PG8_SCHED __builtin_amdgcn_sched_barrier(0)
;     ...
;             PG8_LDB(B0, 1, 0); PG8_LDB(B1, 1, 1); PG8_SCHED; PG8_LDA(At, 1, 0); PG8_STAGE(PG8_SA(0, 1), a2 + hstepA, voffA);
;             PG8_WAIT_V(8); PG8_WAIT_L(0); PG8_BAR; PG8_MMA(0, 0, At, B0); PG8_MMA(0, 1, At, B1); PG8_BAR; PG8_SCHED;
;             PG8_LDA(At, 1, 1); PG8_STAGE(PG8_SB(1, 0), b3, voffB); PG8_STAGE(PG8_SB(1, 1), b3 + hstepB, voffB); PG8_STAGE(PG8_SA(1, 0), a3, voffA);
;             PG8_WAIT_V(8); PG8_WAIT_L(0); PG8_BAR; PG8_MMA(1, 0, At, B0); PG8_MMA(1, 1, At, B1); PG8_BAR; PG8_SCHED;
	s_add_i32 s27, 0, 0x18000
	s_add_i32 s31, 0, 0x1c000
	v_add_u32_e32 v148, s27, v229
	v_add_u32_e32 v172, s31, v229
	ds_read_b128 v[136:139], v148
	ds_read_b128 v[140:143], v148 offset:1024
	ds_read_b128 v[144:147], v148 offset:2048
	ds_read_b128 v[148:151], v148 offset:3072
	ds_read_b128 v[152:155], v172
	ds_read_b128 v[156:159], v172 offset:1024
	ds_read_b128 v[160:163], v172 offset:2048
	ds_read_b128 v[172:175], v172 offset:3072
	s_add_u32 s8, s8, 0x800
	s_addc_u32 s9, s9, 0
	s_mov_b32 m0, s14
	v_lshl_add_u64 v[214:215], s[8:9], 0, v[246:247]
	ds_read_b128 v[176:179], v231 offset:32768
	ds_read_b128 v[180:183], v231 offset:33792
	ds_read_b128 v[184:187], v231 offset:34816
	ds_read_b128 v[188:191], v231 offset:35840
	ds_read_b128 v[192:195], v231 offset:36864
	ds_read_b128 v[196:199], v231 offset:37888
	ds_read_b128 v[200:203], v231 offset:38912
	ds_read_b128 v[204:207], v231 offset:39936
	global_load_lds_dwordx4 v[214:215], off
	v_lshl_add_u64 v[214:215], s[8:9], 0, v[248:249]
	s_mov_b32 m0, s15
	s_nop 0
	global_load_lds_dwordx4 v[214:215], off
	s_waitcnt vmcnt(8)
	s_waitcnt lgkmcnt(0)
	s_barrier
	s_waitcnt lgkmcnt(0)
	v_mfma_f32_16x16x32_bf16 v[126:129], v[136:139], v[176:179], v[126:129]
	v_mfma_f32_16x16x32_bf16 v[122:125], v[144:147], v[176:179], v[122:125]
	v_mfma_f32_16x16x32_bf16 v[110:113], v[136:139], v[184:187], v[110:113]
	v_mfma_f32_16x16x32_bf16 v[106:109], v[144:147], v[184:187], v[106:109]
	v_mfma_f32_16x16x32_bf16 v[94:97], v[136:139], v[192:195], v[94:97]
	v_mfma_f32_16x16x32_bf16 v[90:93], v[144:147], v[192:195], v[90:93]
	v_mfma_f32_16x16x32_bf16 v[78:81], v[136:139], v[200:203], v[78:81]
	v_mfma_f32_16x16x32_bf16 v[74:77], v[144:147], v[200:203], v[74:77]
	v_mfma_f32_16x16x32_bf16 v[126:129], v[140:143], v[180:183], v[126:129]
	v_mfma_f32_16x16x32_bf16 v[122:125], v[148:151], v[180:183], v[122:125]
	v_mfma_f32_16x16x32_bf16 v[110:113], v[140:143], v[188:191], v[110:113]
	v_mfma_f32_16x16x32_bf16 v[106:109], v[148:151], v[188:191], v[106:109]
	v_mfma_f32_16x16x32_bf16 v[94:97], v[140:143], v[196:199], v[94:97]
	v_mfma_f32_16x16x32_bf16 v[90:93], v[148:151], v[196:199], v[90:93]
	v_mfma_f32_16x16x32_bf16 v[78:81], v[140:143], v[204:207], v[78:81]
	v_mfma_f32_16x16x32_bf16 v[74:77], v[148:151], v[204:207], v[74:77]
	v_mfma_f32_16x16x32_bf16 v[118:121], v[152:155], v[176:179], v[118:121]
	v_mfma_f32_16x16x32_bf16 v[114:117], v[160:163], v[176:179], v[114:117]
	v_mfma_f32_16x16x32_bf16 v[102:105], v[152:155], v[184:187], v[102:105]
	v_mfma_f32_16x16x32_bf16 v[98:101], v[160:163], v[184:187], v[98:101]
	v_mfma_f32_16x16x32_bf16 v[86:89], v[152:155], v[192:195], v[86:89]
	v_mfma_f32_16x16x32_bf16 v[82:85], v[160:163], v[192:195], v[82:85]
	v_mfma_f32_16x16x32_bf16 v[70:73], v[152:155], v[200:203], v[70:73]
	v_mfma_f32_16x16x32_bf16 v[66:69], v[160:163], v[200:203], v[66:69]
	v_mfma_f32_16x16x32_bf16 v[118:121], v[156:159], v[180:183], v[118:121]
	v_mfma_f32_16x16x32_bf16 v[114:117], v[172:175], v[180:183], v[114:117]
	v_mfma_f32_16x16x32_bf16 v[102:105], v[156:159], v[188:191], v[102:105]
	v_mfma_f32_16x16x32_bf16 v[98:101], v[172:175], v[188:191], v[98:101]
	v_mfma_f32_16x16x32_bf16 v[86:89], v[156:159], v[196:199], v[86:89]
	v_mfma_f32_16x16x32_bf16 v[82:85], v[172:175], v[196:199], v[82:85]
	v_mfma_f32_16x16x32_bf16 v[70:73], v[156:159], v[204:207], v[70:73]
	v_mfma_f32_16x16x32_bf16 v[66:69], v[172:175], v[204:207], v[66:69]
	s_barrier
	s_add_i32 s8, s27, s0
	v_lshl_add_u64 v[164:165], v[164:165], 0, s[62:63]
	s_mov_b32 m0, s8
	ds_read_b128 v[176:179], v231 offset:49152
	ds_read_b128 v[180:183], v231 offset:50176
	ds_read_b128 v[184:187], v231 offset:51200
	ds_read_b128 v[188:191], v231 offset:52224
	ds_read_b128 v[192:195], v231 offset:53248
	ds_read_b128 v[196:199], v231 offset:54272
	ds_read_b128 v[200:203], v231 offset:55296
	ds_read_b128 v[204:207], v231 offset:56320
	global_load_lds_dwordx4 v[164:165], off
	v_lshl_add_u64 v[164:165], v[168:169], 0, s[62:63]
	s_add_i32 m0, s8, 0x2000
	s_add_i32 s8, s31, s0
	global_load_lds_dwordx4 v[164:165], off
	v_lshl_add_u64 v[164:165], v[170:171], 0, s[62:63]
	s_mov_b32 m0, s8
	s_nop 0
	global_load_lds_dwordx4 v[164:165], off
	v_lshl_add_u64 v[164:165], v[208:209], 0, s[62:63]
	s_add_i32 m0, s8, 0x2000
	s_nop 0
	global_load_lds_dwordx4 v[164:165], off
	v_lshl_add_u64 v[164:165], v[210:211], 0, v[244:245]
	s_mov_b32 m0, s17
	s_nop 0
	global_load_lds_dwordx4 v[164:165], off
	v_lshl_add_u64 v[164:165], v[212:213], 0, v[244:245]
	s_mov_b32 m0, s18
	s_nop 0
	global_load_lds_dwordx4 v[164:165], off
	s_waitcnt vmcnt(8)
	s_waitcnt lgkmcnt(0)
	s_barrier
	s_waitcnt lgkmcnt(0)
	v_mfma_f32_16x16x32_bf16 v[62:65], v[136:139], v[176:179], v[62:65]
	v_mfma_f32_16x16x32_bf16 v[58:61], v[144:147], v[176:179], v[58:61]
	v_mfma_f32_16x16x32_bf16 v[46:49], v[136:139], v[184:187], v[46:49]
	v_mfma_f32_16x16x32_bf16 v[42:45], v[144:147], v[184:187], v[42:45]
	v_mfma_f32_16x16x32_bf16 v[30:33], v[136:139], v[192:195], v[30:33]
	v_mfma_f32_16x16x32_bf16 v[26:29], v[144:147], v[192:195], v[26:29]
	v_mfma_f32_16x16x32_bf16 v[14:17], v[136:139], v[200:203], v[14:17]
	v_mfma_f32_16x16x32_bf16 v[10:13], v[144:147], v[200:203], v[10:13]
	v_mfma_f32_16x16x32_bf16 v[62:65], v[140:143], v[180:183], v[62:65]
	v_mfma_f32_16x16x32_bf16 v[58:61], v[148:151], v[180:183], v[58:61]
	v_mfma_f32_16x16x32_bf16 v[46:49], v[140:143], v[188:191], v[46:49]
	v_mfma_f32_16x16x32_bf16 v[42:45], v[148:151], v[188:191], v[42:45]
	v_mfma_f32_16x16x32_bf16 v[30:33], v[140:143], v[196:199], v[30:33]
	v_mfma_f32_16x16x32_bf16 v[26:29], v[148:151], v[196:199], v[26:29]
	v_mfma_f32_16x16x32_bf16 v[14:17], v[140:143], v[204:207], v[14:17]
	v_mfma_f32_16x16x32_bf16 v[10:13], v[148:151], v[204:207], v[10:13]
	v_mfma_f32_16x16x32_bf16 v[54:57], v[152:155], v[176:179], v[54:57]
	v_mfma_f32_16x16x32_bf16 v[50:53], v[160:163], v[176:179], v[50:53]
	v_mfma_f32_16x16x32_bf16 v[38:41], v[152:155], v[184:187], v[38:41]
	v_mfma_f32_16x16x32_bf16 v[34:37], v[160:163], v[184:187], v[34:37]
	v_mfma_f32_16x16x32_bf16 v[22:25], v[152:155], v[192:195], v[22:25]
	v_mfma_f32_16x16x32_bf16 v[18:21], v[160:163], v[192:195], v[18:21]
	v_mfma_f32_16x16x32_bf16 v[6:9], v[152:155], v[200:203], v[6:9]
	v_mfma_f32_16x16x32_bf16 v[2:5], v[160:163], v[200:203], v[2:5]
	v_mfma_f32_16x16x32_bf16 v[54:57], v[156:159], v[180:183], v[54:57]
	v_mfma_f32_16x16x32_bf16 v[50:53], v[172:175], v[180:183], v[50:53]
	v_mfma_f32_16x16x32_bf16 v[38:41], v[156:159], v[188:191], v[38:41]
	v_mfma_f32_16x16x32_bf16 v[34:37], v[172:175], v[188:191], v[34:37]
	v_mfma_f32_16x16x32_bf16 v[22:25], v[156:159], v[196:199], v[22:25]
	v_mfma_f32_16x16x32_bf16 v[18:21], v[172:175], v[196:199], v[18:21]
	v_mfma_f32_16x16x32_bf16 v[6:9], v[156:159], v[204:207], v[6:9]
	v_mfma_f32_16x16x32_bf16 v[2:5], v[172:175], v[204:207], v[2:5]
	s_barrier
	s_add_u32 s10, s10, 0x100
	s_addc_u32 s11, s11, 0
	s_add_u32 s6, s6, 0x400000
	s_addc_u32 s7, s7, 0
	s_cmp_ge_i32 s25, s13
	s_mov_b32 s8, s25
	s_cbranch_scc0 .LBB0_752
